# sigmoid epilogues: 11-instruction IEEE division sequence replaced by v_rcp_f32 (f32, 1 ulp, result rounded to bf16 as before); hazard nops re-derived
# speedup vs baseline: 1.0334x; 1.0155x over previous
.LBB0_107:
	v_mul_f32_e32 v132, 0xbfb8aa3b, v115
	v_exp_f32_e32 v132, v132
	s_nop 0
	v_add_f32_e32 v132, 1.0, v132
	v_rcp_f32_e32 v132, v132
	s_nop 0
	v_mul_f32_e32 v132, v115, v132

.LBB0_116:
	v_mul_f32_e32 v133, 0xbfb8aa3b, v119
	v_exp_f32_e32 v133, v133
	s_nop 0
	v_add_f32_e32 v133, 1.0, v133
	v_rcp_f32_e32 v133, v133
	s_nop 0
	v_mul_f32_e32 v133, v119, v133

.LBB0_125:
	v_mul_f32_e32 v133, 0xbfb8aa3b, v123
	v_exp_f32_e32 v133, v133
	s_nop 0
	v_add_f32_e32 v133, 1.0, v133
	v_rcp_f32_e32 v133, v133
	s_nop 0
	v_mul_f32_e32 v133, v123, v133

.LBB0_134:
	v_mul_f32_e32 v133, 0xbfb8aa3b, v127
	v_exp_f32_e32 v133, v133
	s_nop 0
	v_add_f32_e32 v133, 1.0, v133
	v_rcp_f32_e32 v133, v133
	s_nop 0
	v_mul_f32_e32 v133, v127, v133

.LBB0_143:
	v_mul_f32_e32 v133, 0xbfb8aa3b, v99
	v_exp_f32_e32 v133, v133
	s_nop 0
	v_add_f32_e32 v133, 1.0, v133
	v_rcp_f32_e32 v133, v133
	s_nop 0
	v_mul_f32_e32 v133, v99, v133

.LBB0_152:
	v_mul_f32_e32 v133, 0xbfb8aa3b, v103
	v_exp_f32_e32 v133, v133
	s_nop 0
	v_add_f32_e32 v133, 1.0, v133
	v_rcp_f32_e32 v133, v133
	s_nop 0
	v_mul_f32_e32 v133, v103, v133

.LBB0_161:
	v_mul_f32_e32 v133, 0xbfb8aa3b, v107
	v_exp_f32_e32 v133, v133
	s_nop 0
	v_add_f32_e32 v133, 1.0, v133
	v_rcp_f32_e32 v133, v133
	s_nop 0
	v_mul_f32_e32 v133, v107, v133

.LBB0_170:
	v_mul_f32_e32 v133, 0xbfb8aa3b, v111
	v_exp_f32_e32 v133, v133
	s_nop 0
	v_add_f32_e32 v133, 1.0, v133
	v_rcp_f32_e32 v133, v133
	s_nop 0
	v_mul_f32_e32 v133, v111, v133

.LBB0_179:
	v_mul_f32_e32 v133, 0xbfb8aa3b, v83
	v_exp_f32_e32 v133, v133
	s_nop 0
	v_add_f32_e32 v133, 1.0, v133
	v_rcp_f32_e32 v133, v133
	s_nop 0
	v_mul_f32_e32 v133, v83, v133

.LBB0_188:
	v_mul_f32_e32 v133, 0xbfb8aa3b, v87
	v_exp_f32_e32 v133, v133
	s_nop 0
	v_add_f32_e32 v133, 1.0, v133
	v_rcp_f32_e32 v133, v133
	s_nop 0
	v_mul_f32_e32 v133, v87, v133

.LBB0_197:
	v_mul_f32_e32 v133, 0xbfb8aa3b, v91
	v_exp_f32_e32 v133, v133
	s_nop 0
	v_add_f32_e32 v133, 1.0, v133
	v_rcp_f32_e32 v133, v133
	s_nop 0
	v_mul_f32_e32 v133, v91, v133

.LBB0_206:
	v_mul_f32_e32 v133, 0xbfb8aa3b, v95
	v_exp_f32_e32 v133, v133
	s_nop 0
	v_add_f32_e32 v133, 1.0, v133
	v_rcp_f32_e32 v133, v133
	s_nop 0
	v_mul_f32_e32 v133, v95, v133

.LBB0_215:
	v_mul_f32_e32 v133, 0xbfb8aa3b, v67
	v_exp_f32_e32 v133, v133
	s_nop 0
	v_add_f32_e32 v133, 1.0, v133
	v_rcp_f32_e32 v133, v133
	s_nop 0
	v_mul_f32_e32 v133, v67, v133

.LBB0_224:
	v_mul_f32_e32 v133, 0xbfb8aa3b, v71
	v_exp_f32_e32 v133, v133
	s_nop 0
	v_add_f32_e32 v133, 1.0, v133
	v_rcp_f32_e32 v133, v133
	s_nop 0
	v_mul_f32_e32 v133, v71, v133

.LBB0_233:
	v_mul_f32_e32 v133, 0xbfb8aa3b, v75
	v_exp_f32_e32 v133, v133
	s_nop 0
	v_add_f32_e32 v133, 1.0, v133
	v_rcp_f32_e32 v133, v133
	s_nop 0
	v_mul_f32_e32 v133, v75, v133

.LBB0_242:
	v_mul_f32_e32 v133, 0xbfb8aa3b, v79
	v_exp_f32_e32 v133, v133
	s_nop 0
	v_add_f32_e32 v133, 1.0, v133
	v_rcp_f32_e32 v133, v133
	s_nop 0
	v_mul_f32_e32 v133, v79, v133

.LBB0_251:
	v_mul_f32_e32 v133, 0xbfb8aa3b, v51
	v_exp_f32_e32 v133, v133
	s_nop 0
	v_add_f32_e32 v133, 1.0, v133
	v_rcp_f32_e32 v133, v133
	s_nop 0
	v_mul_f32_e32 v133, v51, v133

.LBB0_260:
	v_mul_f32_e32 v133, 0xbfb8aa3b, v55
	v_exp_f32_e32 v133, v133
	s_nop 0
	v_add_f32_e32 v133, 1.0, v133
	v_rcp_f32_e32 v133, v133
	s_nop 0
	v_mul_f32_e32 v133, v55, v133

.LBB0_269:
	v_mul_f32_e32 v133, 0xbfb8aa3b, v59
	v_exp_f32_e32 v133, v133
	s_nop 0
	v_add_f32_e32 v133, 1.0, v133
	v_rcp_f32_e32 v133, v133
	s_nop 0
	v_mul_f32_e32 v133, v59, v133

.LBB0_278:
	v_mul_f32_e32 v133, 0xbfb8aa3b, v63
	v_exp_f32_e32 v133, v133
	s_nop 0
	v_add_f32_e32 v133, 1.0, v133
	v_rcp_f32_e32 v133, v133
	s_nop 0
	v_mul_f32_e32 v133, v63, v133

.LBB0_287:
	v_mul_f32_e32 v133, 0xbfb8aa3b, v35
	v_exp_f32_e32 v133, v133
	s_nop 0
	v_add_f32_e32 v133, 1.0, v133
	v_rcp_f32_e32 v133, v133
	s_nop 0
	v_mul_f32_e32 v133, v35, v133

.LBB0_296:
	v_mul_f32_e32 v133, 0xbfb8aa3b, v39
	v_exp_f32_e32 v133, v133
	s_nop 0
	v_add_f32_e32 v133, 1.0, v133
	v_rcp_f32_e32 v133, v133
	s_nop 0
	v_mul_f32_e32 v133, v39, v133

.LBB0_305:
	v_mul_f32_e32 v133, 0xbfb8aa3b, v43
	v_exp_f32_e32 v133, v133
	s_nop 0
	v_add_f32_e32 v133, 1.0, v133
	v_rcp_f32_e32 v133, v133
	s_nop 0
	v_mul_f32_e32 v133, v43, v133

.LBB0_314:
	v_mul_f32_e32 v133, 0xbfb8aa3b, v47
	v_exp_f32_e32 v133, v133
	s_nop 0
	v_add_f32_e32 v133, 1.0, v133
	v_rcp_f32_e32 v133, v133
	s_nop 0
	v_mul_f32_e32 v133, v47, v133

.LBB0_323:
	v_mul_f32_e32 v133, 0xbfb8aa3b, v19
	v_exp_f32_e32 v133, v133
	s_nop 0
	v_add_f32_e32 v133, 1.0, v133
	v_rcp_f32_e32 v133, v133
	s_nop 0
	v_mul_f32_e32 v133, v19, v133

.LBB0_332:
	v_mul_f32_e32 v133, 0xbfb8aa3b, v23
	v_exp_f32_e32 v133, v133
	s_nop 0
	v_add_f32_e32 v133, 1.0, v133
	v_rcp_f32_e32 v133, v133
	s_nop 0
	v_mul_f32_e32 v133, v23, v133

.LBB0_341:
	v_mul_f32_e32 v133, 0xbfb8aa3b, v27
	v_exp_f32_e32 v133, v133
	s_nop 0
	v_add_f32_e32 v133, 1.0, v133
	v_rcp_f32_e32 v133, v133
	s_nop 0
	v_mul_f32_e32 v133, v27, v133

.LBB0_350:
	v_mul_f32_e32 v133, 0xbfb8aa3b, v31
	v_exp_f32_e32 v133, v133
	s_nop 0
	v_add_f32_e32 v133, 1.0, v133
	v_rcp_f32_e32 v133, v133
	s_nop 0
	v_mul_f32_e32 v133, v31, v133

.LBB0_359:
	v_mul_f32_e32 v133, 0xbfb8aa3b, v3
	v_exp_f32_e32 v133, v133
	s_nop 0
	v_add_f32_e32 v133, 1.0, v133
	v_rcp_f32_e32 v133, v133
	s_nop 0
	v_mul_f32_e32 v133, v3, v133

.LBB0_368:
	v_mul_f32_e32 v133, 0xbfb8aa3b, v7
	v_exp_f32_e32 v133, v133
	s_nop 0
	v_add_f32_e32 v133, 1.0, v133
	v_rcp_f32_e32 v133, v133
	s_nop 0
	v_mul_f32_e32 v133, v7, v133

.LBB0_377:
	v_mul_f32_e32 v133, 0xbfb8aa3b, v11
	v_exp_f32_e32 v133, v133
	s_nop 0
	v_add_f32_e32 v133, 1.0, v133
	v_rcp_f32_e32 v133, v133
	s_nop 0
	v_mul_f32_e32 v133, v11, v133

.LBB0_386:
	v_mul_f32_e32 v133, 0xbfb8aa3b, v15
	v_exp_f32_e32 v133, v133
	s_nop 0
	v_add_f32_e32 v133, 1.0, v133
	v_rcp_f32_e32 v133, v133
	s_nop 0
	v_mul_f32_e32 v133, v15, v133

.LBB0_492:
	v_mul_f32_e32 v128, 0xbfb8aa3b, v112
	v_exp_f32_e32 v128, v128
	s_nop 0
	v_add_f32_e32 v128, 1.0, v128
	v_rcp_f32_e32 v128, v128
	s_nop 0
	v_mul_f32_e32 v128, v112, v128
	s_cmp_lt_i32 s44, 1
	s_mov_b64 s[42:43], -1
	s_cbranch_scc1 .LBB0_102

.LBB0_496:
	v_mul_f32_e32 v128, 0xbfb8aa3b, v116
	v_exp_f32_e32 v128, v128
	s_nop 0
	v_add_f32_e32 v128, 1.0, v128
	v_rcp_f32_e32 v128, v128
	s_nop 0
	v_mul_f32_e32 v128, v116, v128
	s_cmp_lt_i32 s44, 1
	s_mov_b64 s[42:43], -1
	s_cbranch_scc1 .LBB0_111

.LBB0_500:
	v_mul_f32_e32 v128, 0xbfb8aa3b, v120
	v_exp_f32_e32 v128, v128
	s_nop 0
	v_add_f32_e32 v128, 1.0, v128
	v_rcp_f32_e32 v128, v128
	s_nop 0
	v_mul_f32_e32 v128, v120, v128
	s_cmp_lt_i32 s44, 1
	s_mov_b64 s[42:43], -1
	s_cbranch_scc1 .LBB0_120

.LBB0_504:
	v_mul_f32_e32 v128, 0xbfb8aa3b, v124
	v_exp_f32_e32 v128, v128
	s_nop 0
	v_add_f32_e32 v128, 1.0, v128
	v_rcp_f32_e32 v128, v128
	s_nop 0
	v_mul_f32_e32 v128, v124, v128
	s_cmp_lt_i32 s44, 1
	s_mov_b64 s[42:43], -1
	s_cbranch_scc1 .LBB0_129

.LBB0_508:
	v_mul_f32_e32 v128, 0xbfb8aa3b, v96
	v_exp_f32_e32 v128, v128
	s_nop 0
	v_add_f32_e32 v128, 1.0, v128
	v_rcp_f32_e32 v128, v128
	s_nop 0
	v_mul_f32_e32 v128, v96, v128
	s_cmp_lt_i32 s44, 1
	s_mov_b64 s[42:43], -1
	s_cbranch_scc1 .LBB0_138

.LBB0_512:
	v_mul_f32_e32 v128, 0xbfb8aa3b, v100
	v_exp_f32_e32 v128, v128
	s_nop 0
	v_add_f32_e32 v128, 1.0, v128
	v_rcp_f32_e32 v128, v128
	s_nop 0
	v_mul_f32_e32 v128, v100, v128
	s_cmp_lt_i32 s44, 1
	s_mov_b64 s[42:43], -1
	s_cbranch_scc1 .LBB0_147

.LBB0_516:
	v_mul_f32_e32 v128, 0xbfb8aa3b, v104
	v_exp_f32_e32 v128, v128
	s_nop 0
	v_add_f32_e32 v128, 1.0, v128
	v_rcp_f32_e32 v128, v128
	s_nop 0
	v_mul_f32_e32 v128, v104, v128
	s_cmp_lt_i32 s44, 1
	s_mov_b64 s[42:43], -1
	s_cbranch_scc1 .LBB0_156

.LBB0_520:
	v_mul_f32_e32 v128, 0xbfb8aa3b, v108
	v_exp_f32_e32 v128, v128
	s_nop 0
	v_add_f32_e32 v128, 1.0, v128
	v_rcp_f32_e32 v128, v128
	s_nop 0
	v_mul_f32_e32 v128, v108, v128
	s_cmp_lt_i32 s44, 1
	s_mov_b64 s[42:43], -1
	s_cbranch_scc1 .LBB0_165

.LBB0_524:
	v_mul_f32_e32 v128, 0xbfb8aa3b, v80
	v_exp_f32_e32 v128, v128
	s_nop 0
	v_add_f32_e32 v128, 1.0, v128
	v_rcp_f32_e32 v128, v128
	s_nop 0
	v_mul_f32_e32 v128, v80, v128
	s_cmp_lt_i32 s44, 1
	s_mov_b64 s[42:43], -1
	s_cbranch_scc1 .LBB0_174

.LBB0_528:
	v_mul_f32_e32 v128, 0xbfb8aa3b, v84
	v_exp_f32_e32 v128, v128
	s_nop 0
	v_add_f32_e32 v128, 1.0, v128
	v_rcp_f32_e32 v128, v128
	s_nop 0
	v_mul_f32_e32 v128, v84, v128
	s_cmp_lt_i32 s44, 1
	s_mov_b64 s[42:43], -1
	s_cbranch_scc1 .LBB0_183

.LBB0_532:
	v_mul_f32_e32 v128, 0xbfb8aa3b, v88
	v_exp_f32_e32 v128, v128
	s_nop 0
	v_add_f32_e32 v128, 1.0, v128
	v_rcp_f32_e32 v128, v128
	s_nop 0
	v_mul_f32_e32 v128, v88, v128
	s_cmp_lt_i32 s44, 1
	s_mov_b64 s[42:43], -1
	s_cbranch_scc1 .LBB0_192

.LBB0_536:
	v_mul_f32_e32 v128, 0xbfb8aa3b, v92
	v_exp_f32_e32 v128, v128
	s_nop 0
	v_add_f32_e32 v128, 1.0, v128
	v_rcp_f32_e32 v128, v128
	s_nop 0
	v_mul_f32_e32 v128, v92, v128
	s_cmp_lt_i32 s44, 1
	s_mov_b64 s[42:43], -1
	s_cbranch_scc1 .LBB0_201

.LBB0_540:
	v_mul_f32_e32 v128, 0xbfb8aa3b, v64
	v_exp_f32_e32 v128, v128
	s_nop 0
	v_add_f32_e32 v128, 1.0, v128
	v_rcp_f32_e32 v128, v128
	s_nop 0
	v_mul_f32_e32 v128, v64, v128
	s_cmp_lt_i32 s44, 1
	s_mov_b64 s[42:43], -1
	s_cbranch_scc1 .LBB0_210

.LBB0_544:
	v_mul_f32_e32 v128, 0xbfb8aa3b, v68
	v_exp_f32_e32 v128, v128
	s_nop 0
	v_add_f32_e32 v128, 1.0, v128
	v_rcp_f32_e32 v128, v128
	s_nop 0
	v_mul_f32_e32 v128, v68, v128
	s_cmp_lt_i32 s44, 1
	s_mov_b64 s[42:43], -1
	s_cbranch_scc1 .LBB0_219

.LBB0_548:
	v_mul_f32_e32 v128, 0xbfb8aa3b, v72
	v_exp_f32_e32 v128, v128
	s_nop 0
	v_add_f32_e32 v128, 1.0, v128
	v_rcp_f32_e32 v128, v128
	s_nop 0
	v_mul_f32_e32 v128, v72, v128
	s_cmp_lt_i32 s44, 1
	s_mov_b64 s[42:43], -1
	s_cbranch_scc1 .LBB0_228

.LBB0_552:
	v_mul_f32_e32 v128, 0xbfb8aa3b, v76
	v_exp_f32_e32 v128, v128
	s_nop 0
	v_add_f32_e32 v128, 1.0, v128
	v_rcp_f32_e32 v128, v128
	s_nop 0
	v_mul_f32_e32 v128, v76, v128
	s_cmp_lt_i32 s44, 1
	s_mov_b64 s[42:43], -1
	s_cbranch_scc1 .LBB0_237

.LBB0_556:
	v_mul_f32_e32 v128, 0xbfb8aa3b, v48
	v_exp_f32_e32 v128, v128
	s_nop 0
	v_add_f32_e32 v128, 1.0, v128
	v_rcp_f32_e32 v128, v128
	s_nop 0
	v_mul_f32_e32 v128, v48, v128
	s_cmp_lt_i32 s44, 1
	s_mov_b64 s[42:43], -1
	s_cbranch_scc1 .LBB0_246

.LBB0_560:
	v_mul_f32_e32 v128, 0xbfb8aa3b, v52
	v_exp_f32_e32 v128, v128
	s_nop 0
	v_add_f32_e32 v128, 1.0, v128
	v_rcp_f32_e32 v128, v128
	s_nop 0
	v_mul_f32_e32 v128, v52, v128
	s_cmp_lt_i32 s44, 1
	s_mov_b64 s[42:43], -1
	s_cbranch_scc1 .LBB0_255

.LBB0_564:
	v_mul_f32_e32 v128, 0xbfb8aa3b, v56
	v_exp_f32_e32 v128, v128
	s_nop 0
	v_add_f32_e32 v128, 1.0, v128
	v_rcp_f32_e32 v128, v128
	s_nop 0
	v_mul_f32_e32 v128, v56, v128
	s_cmp_lt_i32 s44, 1
	s_mov_b64 s[42:43], -1
	s_cbranch_scc1 .LBB0_264

.LBB0_568:
	v_mul_f32_e32 v128, 0xbfb8aa3b, v60
	v_exp_f32_e32 v128, v128
	s_nop 0
	v_add_f32_e32 v128, 1.0, v128
	v_rcp_f32_e32 v128, v128
	s_nop 0
	v_mul_f32_e32 v128, v60, v128
	s_cmp_lt_i32 s44, 1
	s_mov_b64 s[42:43], -1
	s_cbranch_scc1 .LBB0_273

.LBB0_572:
	v_mul_f32_e32 v128, 0xbfb8aa3b, v32
	v_exp_f32_e32 v128, v128
	s_nop 0
	v_add_f32_e32 v128, 1.0, v128
	v_rcp_f32_e32 v128, v128
	s_nop 0
	v_mul_f32_e32 v128, v32, v128
	s_cmp_lt_i32 s44, 1
	s_mov_b64 s[42:43], -1
	s_cbranch_scc1 .LBB0_282

.LBB0_576:
	v_mul_f32_e32 v128, 0xbfb8aa3b, v36
	v_exp_f32_e32 v128, v128
	s_nop 0
	v_add_f32_e32 v128, 1.0, v128
	v_rcp_f32_e32 v128, v128
	s_nop 0
	v_mul_f32_e32 v128, v36, v128
	s_cmp_lt_i32 s44, 1
	s_mov_b64 s[42:43], -1
	s_cbranch_scc1 .LBB0_291

.LBB0_580:
	v_mul_f32_e32 v128, 0xbfb8aa3b, v40
	v_exp_f32_e32 v128, v128
	s_nop 0
	v_add_f32_e32 v128, 1.0, v128
	v_rcp_f32_e32 v128, v128
	s_nop 0
	v_mul_f32_e32 v128, v40, v128
	s_cmp_lt_i32 s44, 1
	s_mov_b64 s[42:43], -1
	s_cbranch_scc1 .LBB0_300

.LBB0_584:
	v_mul_f32_e32 v128, 0xbfb8aa3b, v44
	v_exp_f32_e32 v128, v128
	s_nop 0
	v_add_f32_e32 v128, 1.0, v128
	v_rcp_f32_e32 v128, v128
	s_nop 0
	v_mul_f32_e32 v128, v44, v128
	s_cmp_lt_i32 s44, 1
	s_mov_b64 s[42:43], -1
	s_cbranch_scc1 .LBB0_309

.LBB0_588:
	v_mul_f32_e32 v128, 0xbfb8aa3b, v16
	v_exp_f32_e32 v128, v128
	s_nop 0
	v_add_f32_e32 v128, 1.0, v128
	v_rcp_f32_e32 v128, v128
	s_nop 0
	v_mul_f32_e32 v128, v16, v128
	s_cmp_lt_i32 s44, 1
	s_mov_b64 s[42:43], -1
	s_cbranch_scc1 .LBB0_318

.LBB0_592:
	v_mul_f32_e32 v128, 0xbfb8aa3b, v20
	v_exp_f32_e32 v128, v128
	s_nop 0
	v_add_f32_e32 v128, 1.0, v128
	v_rcp_f32_e32 v128, v128
	s_nop 0
	v_mul_f32_e32 v128, v20, v128
	s_cmp_lt_i32 s44, 1
	s_mov_b64 s[42:43], -1
	s_cbranch_scc1 .LBB0_327

.LBB0_596:
	v_mul_f32_e32 v128, 0xbfb8aa3b, v24
	v_exp_f32_e32 v128, v128
	s_nop 0
	v_add_f32_e32 v128, 1.0, v128
	v_rcp_f32_e32 v128, v128
	s_nop 0
	v_mul_f32_e32 v128, v24, v128
	s_cmp_lt_i32 s44, 1
	s_mov_b64 s[42:43], -1
	s_cbranch_scc1 .LBB0_336

.LBB0_600:
	v_mul_f32_e32 v128, 0xbfb8aa3b, v28
	v_exp_f32_e32 v128, v128
	s_nop 0
	v_add_f32_e32 v128, 1.0, v128
	v_rcp_f32_e32 v128, v128
	s_nop 0
	v_mul_f32_e32 v128, v28, v128
	s_cmp_lt_i32 s44, 1
	s_mov_b64 s[42:43], -1
	s_cbranch_scc1 .LBB0_345

.LBB0_604:
	v_mul_f32_e32 v128, 0xbfb8aa3b, v0
	v_exp_f32_e32 v128, v128
	s_nop 0
	v_add_f32_e32 v128, 1.0, v128
	v_rcp_f32_e32 v128, v128
	s_nop 0
	v_mul_f32_e32 v128, v0, v128
	s_cmp_lt_i32 s44, 1
	s_mov_b64 s[42:43], -1
	s_cbranch_scc1 .LBB0_354

.LBB0_608:
	v_mul_f32_e32 v128, 0xbfb8aa3b, v4
	v_exp_f32_e32 v128, v128
	s_nop 0
	v_add_f32_e32 v128, 1.0, v128
	v_rcp_f32_e32 v128, v128
	s_nop 0
	v_mul_f32_e32 v128, v4, v128
	s_cmp_lt_i32 s44, 1
	s_mov_b64 s[42:43], -1
	s_cbranch_scc1 .LBB0_363

.LBB0_612:
	v_mul_f32_e32 v128, 0xbfb8aa3b, v8
	v_exp_f32_e32 v128, v128
	s_nop 0
	v_add_f32_e32 v128, 1.0, v128
	v_rcp_f32_e32 v128, v128
	s_nop 0
	v_mul_f32_e32 v128, v8, v128
	s_cmp_lt_i32 s44, 1
	s_mov_b64 s[42:43], -1
	s_cbranch_scc1 .LBB0_372

.LBB0_616:
	v_mul_f32_e32 v128, 0xbfb8aa3b, v12
	v_exp_f32_e32 v128, v128
	s_nop 0
	v_add_f32_e32 v128, 1.0, v128
	v_rcp_f32_e32 v128, v128
	s_nop 0
	v_mul_f32_e32 v128, v12, v128
	s_cmp_lt_i32 s44, 1
	s_mov_b64 s[42:43], -1
	s_cbranch_scc1 .LBB0_381

.LBB0_620:
	v_mul_f32_e32 v129, 0xbfb8aa3b, v113
	v_exp_f32_e32 v129, v129
	s_nop 0
	v_add_f32_e32 v129, 1.0, v129
	v_rcp_f32_e32 v129, v129
	s_nop 0
	v_mul_f32_e32 v129, v113, v129
	s_cmp_lt_i32 s44, 1
	s_mov_b64 s[42:43], -1
	s_cbranch_scc1 .LBB0_104

.LBB0_624:
	v_mul_f32_e32 v129, 0xbfb8aa3b, v117
	v_exp_f32_e32 v129, v129
	s_nop 0
	v_add_f32_e32 v129, 1.0, v129
	v_rcp_f32_e32 v129, v129
	s_nop 0
	v_mul_f32_e32 v129, v117, v129
	s_cmp_lt_i32 s44, 1
	s_mov_b64 s[42:43], -1
	s_cbranch_scc1 .LBB0_113

.LBB0_628:
	v_mul_f32_e32 v129, 0xbfb8aa3b, v121
	v_exp_f32_e32 v129, v129
	s_nop 0
	v_add_f32_e32 v129, 1.0, v129
	v_rcp_f32_e32 v129, v129
	s_nop 0
	v_mul_f32_e32 v129, v121, v129
	s_cmp_lt_i32 s44, 1
	s_mov_b64 s[42:43], -1
	s_cbranch_scc1 .LBB0_122

.LBB0_632:
	v_mul_f32_e32 v129, 0xbfb8aa3b, v125
	v_exp_f32_e32 v129, v129
	s_nop 0
	v_add_f32_e32 v129, 1.0, v129
	v_rcp_f32_e32 v129, v129
	s_nop 0
	v_mul_f32_e32 v129, v125, v129
	s_cmp_lt_i32 s44, 1
	s_mov_b64 s[42:43], -1
	s_cbranch_scc1 .LBB0_131

.LBB0_636:
	v_mul_f32_e32 v129, 0xbfb8aa3b, v97
	v_exp_f32_e32 v129, v129
	s_nop 0
	v_add_f32_e32 v129, 1.0, v129
	v_rcp_f32_e32 v129, v129
	s_nop 0
	v_mul_f32_e32 v129, v97, v129
	s_cmp_lt_i32 s44, 1
	s_mov_b64 s[42:43], -1
	s_cbranch_scc1 .LBB0_140

.LBB0_640:
	v_mul_f32_e32 v129, 0xbfb8aa3b, v101
	v_exp_f32_e32 v129, v129
	s_nop 0
	v_add_f32_e32 v129, 1.0, v129
	v_rcp_f32_e32 v129, v129
	s_nop 0
	v_mul_f32_e32 v129, v101, v129
	s_cmp_lt_i32 s44, 1
	s_mov_b64 s[42:43], -1
	s_cbranch_scc1 .LBB0_149

.LBB0_644:
	v_mul_f32_e32 v129, 0xbfb8aa3b, v105
	v_exp_f32_e32 v129, v129
	s_nop 0
	v_add_f32_e32 v129, 1.0, v129
	v_rcp_f32_e32 v129, v129
	s_nop 0
	v_mul_f32_e32 v129, v105, v129
	s_cmp_lt_i32 s44, 1
	s_mov_b64 s[42:43], -1
	s_cbranch_scc1 .LBB0_158

.LBB0_648:
	v_mul_f32_e32 v129, 0xbfb8aa3b, v109
	v_exp_f32_e32 v129, v129
	s_nop 0
	v_add_f32_e32 v129, 1.0, v129
	v_rcp_f32_e32 v129, v129
	s_nop 0
	v_mul_f32_e32 v129, v109, v129
	s_cmp_lt_i32 s44, 1
	s_mov_b64 s[42:43], -1
	s_cbranch_scc1 .LBB0_167

.LBB0_652:
	v_mul_f32_e32 v129, 0xbfb8aa3b, v81
	v_exp_f32_e32 v129, v129
	s_nop 0
	v_add_f32_e32 v129, 1.0, v129
	v_rcp_f32_e32 v129, v129
	s_nop 0
	v_mul_f32_e32 v129, v81, v129
	s_cmp_lt_i32 s44, 1
	s_mov_b64 s[42:43], -1
	s_cbranch_scc1 .LBB0_176

.LBB0_656:
	v_mul_f32_e32 v129, 0xbfb8aa3b, v85
	v_exp_f32_e32 v129, v129
	s_nop 0
	v_add_f32_e32 v129, 1.0, v129
	v_rcp_f32_e32 v129, v129
	s_nop 0
	v_mul_f32_e32 v129, v85, v129
	s_cmp_lt_i32 s44, 1
	s_mov_b64 s[42:43], -1
	s_cbranch_scc1 .LBB0_185

.LBB0_660:
	v_mul_f32_e32 v129, 0xbfb8aa3b, v89
	v_exp_f32_e32 v129, v129
	s_nop 0
	v_add_f32_e32 v129, 1.0, v129
	v_rcp_f32_e32 v129, v129
	s_nop 0
	v_mul_f32_e32 v129, v89, v129
	s_cmp_lt_i32 s44, 1
	s_mov_b64 s[42:43], -1
	s_cbranch_scc1 .LBB0_194

.LBB0_664:
	v_mul_f32_e32 v129, 0xbfb8aa3b, v93
	v_exp_f32_e32 v129, v129
	s_nop 0
	v_add_f32_e32 v129, 1.0, v129
	v_rcp_f32_e32 v129, v129
	s_nop 0
	v_mul_f32_e32 v129, v93, v129
	s_cmp_lt_i32 s44, 1
	s_mov_b64 s[42:43], -1
	s_cbranch_scc1 .LBB0_203

.LBB0_668:
	v_mul_f32_e32 v129, 0xbfb8aa3b, v65
	v_exp_f32_e32 v129, v129
	s_nop 0
	v_add_f32_e32 v129, 1.0, v129
	v_rcp_f32_e32 v129, v129
	s_nop 0
	v_mul_f32_e32 v129, v65, v129
	s_cmp_lt_i32 s44, 1
	s_mov_b64 s[42:43], -1
	s_cbranch_scc1 .LBB0_212

.LBB0_672:
	v_mul_f32_e32 v129, 0xbfb8aa3b, v69
	v_exp_f32_e32 v129, v129
	s_nop 0
	v_add_f32_e32 v129, 1.0, v129
	v_rcp_f32_e32 v129, v129
	s_nop 0
	v_mul_f32_e32 v129, v69, v129
	s_cmp_lt_i32 s44, 1
	s_mov_b64 s[42:43], -1
	s_cbranch_scc1 .LBB0_221

.LBB0_676:
	v_mul_f32_e32 v129, 0xbfb8aa3b, v73
	v_exp_f32_e32 v129, v129
	s_nop 0
	v_add_f32_e32 v129, 1.0, v129
	v_rcp_f32_e32 v129, v129
	s_nop 0
	v_mul_f32_e32 v129, v73, v129
	s_cmp_lt_i32 s44, 1
	s_mov_b64 s[42:43], -1
	s_cbranch_scc1 .LBB0_230

.LBB0_680:
	v_mul_f32_e32 v129, 0xbfb8aa3b, v77
	v_exp_f32_e32 v129, v129
	s_nop 0
	v_add_f32_e32 v129, 1.0, v129
	v_rcp_f32_e32 v129, v129
	s_nop 0
	v_mul_f32_e32 v129, v77, v129
	s_cmp_lt_i32 s44, 1
	s_mov_b64 s[42:43], -1
	s_cbranch_scc1 .LBB0_239

.LBB0_684:
	v_mul_f32_e32 v129, 0xbfb8aa3b, v49
	v_exp_f32_e32 v129, v129
	s_nop 0
	v_add_f32_e32 v129, 1.0, v129
	v_rcp_f32_e32 v129, v129
	s_nop 0
	v_mul_f32_e32 v129, v49, v129
	s_cmp_lt_i32 s44, 1
	s_mov_b64 s[42:43], -1
	s_cbranch_scc1 .LBB0_248

.LBB0_688:
	v_mul_f32_e32 v129, 0xbfb8aa3b, v53
	v_exp_f32_e32 v129, v129
	s_nop 0
	v_add_f32_e32 v129, 1.0, v129
	v_rcp_f32_e32 v129, v129
	s_nop 0
	v_mul_f32_e32 v129, v53, v129
	s_cmp_lt_i32 s44, 1
	s_mov_b64 s[42:43], -1
	s_cbranch_scc1 .LBB0_257

.LBB0_692:
	v_mul_f32_e32 v129, 0xbfb8aa3b, v57
	v_exp_f32_e32 v129, v129
	s_nop 0
	v_add_f32_e32 v129, 1.0, v129
	v_rcp_f32_e32 v129, v129
	s_nop 0
	v_mul_f32_e32 v129, v57, v129
	s_cmp_lt_i32 s44, 1
	s_mov_b64 s[42:43], -1
	s_cbranch_scc1 .LBB0_266

.LBB0_696:
	v_mul_f32_e32 v129, 0xbfb8aa3b, v61
	v_exp_f32_e32 v129, v129
	s_nop 0
	v_add_f32_e32 v129, 1.0, v129
	v_rcp_f32_e32 v129, v129
	s_nop 0
	v_mul_f32_e32 v129, v61, v129
	s_cmp_lt_i32 s44, 1
	s_mov_b64 s[42:43], -1
	s_cbranch_scc1 .LBB0_275

.LBB0_700:
	v_mul_f32_e32 v129, 0xbfb8aa3b, v33
	v_exp_f32_e32 v129, v129
	s_nop 0
	v_add_f32_e32 v129, 1.0, v129
	v_rcp_f32_e32 v129, v129
	s_nop 0
	v_mul_f32_e32 v129, v33, v129
	s_cmp_lt_i32 s44, 1
	s_mov_b64 s[42:43], -1
	s_cbranch_scc1 .LBB0_284

.LBB0_704:
	v_mul_f32_e32 v129, 0xbfb8aa3b, v37
	v_exp_f32_e32 v129, v129
	s_nop 0
	v_add_f32_e32 v129, 1.0, v129
	v_rcp_f32_e32 v129, v129
	s_nop 0
	v_mul_f32_e32 v129, v37, v129
	s_cmp_lt_i32 s44, 1
	s_mov_b64 s[42:43], -1
	s_cbranch_scc1 .LBB0_293

.LBB0_708:
	v_mul_f32_e32 v129, 0xbfb8aa3b, v41
	v_exp_f32_e32 v129, v129
	s_nop 0
	v_add_f32_e32 v129, 1.0, v129
	v_rcp_f32_e32 v129, v129
	s_nop 0
	v_mul_f32_e32 v129, v41, v129
	s_cmp_lt_i32 s44, 1
	s_mov_b64 s[42:43], -1
	s_cbranch_scc1 .LBB0_302

.LBB0_712:
	v_mul_f32_e32 v129, 0xbfb8aa3b, v45
	v_exp_f32_e32 v129, v129
	s_nop 0
	v_add_f32_e32 v129, 1.0, v129
	v_rcp_f32_e32 v129, v129
	s_nop 0
	v_mul_f32_e32 v129, v45, v129
	s_cmp_lt_i32 s44, 1
	s_mov_b64 s[42:43], -1
	s_cbranch_scc1 .LBB0_311

.LBB0_716:
	v_mul_f32_e32 v129, 0xbfb8aa3b, v17
	v_exp_f32_e32 v129, v129
	s_nop 0
	v_add_f32_e32 v129, 1.0, v129
	v_rcp_f32_e32 v129, v129
	s_nop 0
	v_mul_f32_e32 v129, v17, v129
	s_cmp_lt_i32 s44, 1
	s_mov_b64 s[42:43], -1
	s_cbranch_scc1 .LBB0_320

.LBB0_720:
	v_mul_f32_e32 v129, 0xbfb8aa3b, v21
	v_exp_f32_e32 v129, v129
	s_nop 0
	v_add_f32_e32 v129, 1.0, v129
	v_rcp_f32_e32 v129, v129
	s_nop 0
	v_mul_f32_e32 v129, v21, v129
	s_cmp_lt_i32 s44, 1
	s_mov_b64 s[42:43], -1
	s_cbranch_scc1 .LBB0_329

.LBB0_724:
	v_mul_f32_e32 v129, 0xbfb8aa3b, v25
	v_exp_f32_e32 v129, v129
	s_nop 0
	v_add_f32_e32 v129, 1.0, v129
	v_rcp_f32_e32 v129, v129
	s_nop 0
	v_mul_f32_e32 v129, v25, v129
	s_cmp_lt_i32 s44, 1
	s_mov_b64 s[42:43], -1
	s_cbranch_scc1 .LBB0_338

.LBB0_728:
	v_mul_f32_e32 v129, 0xbfb8aa3b, v29
	v_exp_f32_e32 v129, v129
	s_nop 0
	v_add_f32_e32 v129, 1.0, v129
	v_rcp_f32_e32 v129, v129
	s_nop 0
	v_mul_f32_e32 v129, v29, v129
	s_cmp_lt_i32 s44, 1
	s_mov_b64 s[42:43], -1
	s_cbranch_scc1 .LBB0_347

.LBB0_732:
	v_mul_f32_e32 v129, 0xbfb8aa3b, v1
	v_exp_f32_e32 v129, v129
	s_nop 0
	v_add_f32_e32 v129, 1.0, v129
	v_rcp_f32_e32 v129, v129
	s_nop 0
	v_mul_f32_e32 v129, v1, v129
	s_cmp_lt_i32 s44, 1
	s_mov_b64 s[42:43], -1
	s_cbranch_scc1 .LBB0_356

.LBB0_736:
	v_mul_f32_e32 v129, 0xbfb8aa3b, v5
	v_exp_f32_e32 v129, v129
	s_nop 0
	v_add_f32_e32 v129, 1.0, v129
	v_rcp_f32_e32 v129, v129
	s_nop 0
	v_mul_f32_e32 v129, v5, v129
	s_cmp_lt_i32 s44, 1
	s_mov_b64 s[42:43], -1
	s_cbranch_scc1 .LBB0_365

.LBB0_740:
	v_mul_f32_e32 v129, 0xbfb8aa3b, v9
	v_exp_f32_e32 v129, v129
	s_nop 0
	v_add_f32_e32 v129, 1.0, v129
	v_rcp_f32_e32 v129, v129
	s_nop 0
	v_mul_f32_e32 v129, v9, v129
	s_cmp_lt_i32 s44, 1
	s_mov_b64 s[42:43], -1
	s_cbranch_scc1 .LBB0_374

.LBB0_744:
	v_mul_f32_e32 v129, 0xbfb8aa3b, v13
	v_exp_f32_e32 v129, v129
	s_nop 0
	v_add_f32_e32 v129, 1.0, v129
	v_rcp_f32_e32 v129, v129
	s_nop 0
	v_mul_f32_e32 v129, v13, v129
	s_cmp_lt_i32 s44, 1
	s_mov_b64 s[42:43], -1
	s_cbranch_scc1 .LBB0_383

.LBB0_748:
	v_mul_f32_e32 v131, 0xbfb8aa3b, v114
	v_exp_f32_e32 v131, v131
	s_nop 0
	v_add_f32_e32 v131, 1.0, v131
	v_rcp_f32_e32 v131, v131
	s_nop 0
	v_mul_f32_e32 v131, v114, v131
	s_cmp_lt_i32 s44, 1
	s_mov_b64 s[42:43], -1
	s_cbranch_scc1 .LBB0_106

.LBB0_752:
	v_mul_f32_e32 v132, 0xbfb8aa3b, v118
	v_exp_f32_e32 v132, v132
	s_nop 0
	v_add_f32_e32 v132, 1.0, v132
	v_rcp_f32_e32 v132, v132
	s_nop 0
	v_mul_f32_e32 v132, v118, v132
	s_cmp_lt_i32 s44, 1
	s_mov_b64 s[42:43], -1
	s_cbranch_scc1 .LBB0_115

.LBB0_756:
	v_mul_f32_e32 v132, 0xbfb8aa3b, v122
	v_exp_f32_e32 v132, v132
	s_nop 0
	v_add_f32_e32 v132, 1.0, v132
	v_rcp_f32_e32 v132, v132
	s_nop 0
	v_mul_f32_e32 v132, v122, v132
	s_cmp_lt_i32 s44, 1
	s_mov_b64 s[42:43], -1
	s_cbranch_scc1 .LBB0_124

.LBB0_760:
	v_mul_f32_e32 v132, 0xbfb8aa3b, v126
	v_exp_f32_e32 v132, v132
	s_nop 0
	v_add_f32_e32 v132, 1.0, v132
	v_rcp_f32_e32 v132, v132
	s_nop 0
	v_mul_f32_e32 v132, v126, v132
	s_cmp_lt_i32 s44, 1
	s_mov_b64 s[42:43], -1
	s_cbranch_scc1 .LBB0_133

.LBB0_764:
	v_mul_f32_e32 v132, 0xbfb8aa3b, v98
	v_exp_f32_e32 v132, v132
	s_nop 0
	v_add_f32_e32 v132, 1.0, v132
	v_rcp_f32_e32 v132, v132
	s_nop 0
	v_mul_f32_e32 v132, v98, v132
	s_cmp_lt_i32 s44, 1
	s_mov_b64 s[42:43], -1
	s_cbranch_scc1 .LBB0_142

.LBB0_768:
	v_mul_f32_e32 v132, 0xbfb8aa3b, v102
	v_exp_f32_e32 v132, v132
	s_nop 0
	v_add_f32_e32 v132, 1.0, v132
	v_rcp_f32_e32 v132, v132
	s_nop 0
	v_mul_f32_e32 v132, v102, v132
	s_cmp_lt_i32 s44, 1
	s_mov_b64 s[42:43], -1
	s_cbranch_scc1 .LBB0_151

.LBB0_772:
	v_mul_f32_e32 v132, 0xbfb8aa3b, v106
	v_exp_f32_e32 v132, v132
	s_nop 0
	v_add_f32_e32 v132, 1.0, v132
	v_rcp_f32_e32 v132, v132
	s_nop 0
	v_mul_f32_e32 v132, v106, v132
	s_cmp_lt_i32 s44, 1
	s_mov_b64 s[42:43], -1
	s_cbranch_scc1 .LBB0_160

.LBB0_776:
	v_mul_f32_e32 v132, 0xbfb8aa3b, v110
	v_exp_f32_e32 v132, v132
	s_nop 0
	v_add_f32_e32 v132, 1.0, v132
	v_rcp_f32_e32 v132, v132
	s_nop 0
	v_mul_f32_e32 v132, v110, v132
	s_cmp_lt_i32 s44, 1
	s_mov_b64 s[42:43], -1
	s_cbranch_scc1 .LBB0_169

.LBB0_780:
	v_mul_f32_e32 v132, 0xbfb8aa3b, v82
	v_exp_f32_e32 v132, v132
	s_nop 0
	v_add_f32_e32 v132, 1.0, v132
	v_rcp_f32_e32 v132, v132
	s_nop 0
	v_mul_f32_e32 v132, v82, v132
	s_cmp_lt_i32 s44, 1
	s_mov_b64 s[42:43], -1
	s_cbranch_scc1 .LBB0_178

.LBB0_784:
	v_mul_f32_e32 v132, 0xbfb8aa3b, v86
	v_exp_f32_e32 v132, v132
	s_nop 0
	v_add_f32_e32 v132, 1.0, v132
	v_rcp_f32_e32 v132, v132
	s_nop 0
	v_mul_f32_e32 v132, v86, v132
	s_cmp_lt_i32 s44, 1
	s_mov_b64 s[42:43], -1
	s_cbranch_scc1 .LBB0_187

.LBB0_788:
	v_mul_f32_e32 v132, 0xbfb8aa3b, v90
	v_exp_f32_e32 v132, v132
	s_nop 0
	v_add_f32_e32 v132, 1.0, v132
	v_rcp_f32_e32 v132, v132
	s_nop 0
	v_mul_f32_e32 v132, v90, v132
	s_cmp_lt_i32 s44, 1
	s_mov_b64 s[42:43], -1
	s_cbranch_scc1 .LBB0_196

.LBB0_792:
	v_mul_f32_e32 v132, 0xbfb8aa3b, v94
	v_exp_f32_e32 v132, v132
	s_nop 0
	v_add_f32_e32 v132, 1.0, v132
	v_rcp_f32_e32 v132, v132
	s_nop 0
	v_mul_f32_e32 v132, v94, v132
	s_cmp_lt_i32 s44, 1
	s_mov_b64 s[42:43], -1
	s_cbranch_scc1 .LBB0_205

.LBB0_796:
	v_mul_f32_e32 v132, 0xbfb8aa3b, v66
	v_exp_f32_e32 v132, v132
	s_nop 0
	v_add_f32_e32 v132, 1.0, v132
	v_rcp_f32_e32 v132, v132
	s_nop 0
	v_mul_f32_e32 v132, v66, v132
	s_cmp_lt_i32 s44, 1
	s_mov_b64 s[42:43], -1
	s_cbranch_scc1 .LBB0_214

.LBB0_800:
	v_mul_f32_e32 v132, 0xbfb8aa3b, v70
	v_exp_f32_e32 v132, v132
	s_nop 0
	v_add_f32_e32 v132, 1.0, v132
	v_rcp_f32_e32 v132, v132
	s_nop 0
	v_mul_f32_e32 v132, v70, v132
	s_cmp_lt_i32 s44, 1
	s_mov_b64 s[42:43], -1
	s_cbranch_scc1 .LBB0_223

.LBB0_804:
	v_mul_f32_e32 v132, 0xbfb8aa3b, v74
	v_exp_f32_e32 v132, v132
	s_nop 0
	v_add_f32_e32 v132, 1.0, v132
	v_rcp_f32_e32 v132, v132
	s_nop 0
	v_mul_f32_e32 v132, v74, v132
	s_cmp_lt_i32 s44, 1
	s_mov_b64 s[42:43], -1
	s_cbranch_scc1 .LBB0_232

.LBB0_808:
	v_mul_f32_e32 v132, 0xbfb8aa3b, v78
	v_exp_f32_e32 v132, v132
	s_nop 0
	v_add_f32_e32 v132, 1.0, v132
	v_rcp_f32_e32 v132, v132
	s_nop 0
	v_mul_f32_e32 v132, v78, v132
	s_cmp_lt_i32 s44, 1
	s_mov_b64 s[42:43], -1
	s_cbranch_scc1 .LBB0_241

.LBB0_812:
	v_mul_f32_e32 v132, 0xbfb8aa3b, v50
	v_exp_f32_e32 v132, v132
	s_nop 0
	v_add_f32_e32 v132, 1.0, v132
	v_rcp_f32_e32 v132, v132
	s_nop 0
	v_mul_f32_e32 v132, v50, v132
	s_cmp_lt_i32 s44, 1
	s_mov_b64 s[42:43], -1
	s_cbranch_scc1 .LBB0_250

.LBB0_816:
	v_mul_f32_e32 v132, 0xbfb8aa3b, v54
	v_exp_f32_e32 v132, v132
	s_nop 0
	v_add_f32_e32 v132, 1.0, v132
	v_rcp_f32_e32 v132, v132
	s_nop 0
	v_mul_f32_e32 v132, v54, v132
	s_cmp_lt_i32 s44, 1
	s_mov_b64 s[42:43], -1
	s_cbranch_scc1 .LBB0_259

.LBB0_820:
	v_mul_f32_e32 v132, 0xbfb8aa3b, v58
	v_exp_f32_e32 v132, v132
	s_nop 0
	v_add_f32_e32 v132, 1.0, v132
	v_rcp_f32_e32 v132, v132
	s_nop 0
	v_mul_f32_e32 v132, v58, v132
	s_cmp_lt_i32 s44, 1
	s_mov_b64 s[42:43], -1
	s_cbranch_scc1 .LBB0_268

.LBB0_824:
	v_mul_f32_e32 v132, 0xbfb8aa3b, v62
	v_exp_f32_e32 v132, v132
	s_nop 0
	v_add_f32_e32 v132, 1.0, v132
	v_rcp_f32_e32 v132, v132
	s_nop 0
	v_mul_f32_e32 v132, v62, v132
	s_cmp_lt_i32 s44, 1
	s_mov_b64 s[42:43], -1
	s_cbranch_scc1 .LBB0_277

.LBB0_828:
	v_mul_f32_e32 v132, 0xbfb8aa3b, v34
	v_exp_f32_e32 v132, v132
	s_nop 0
	v_add_f32_e32 v132, 1.0, v132
	v_rcp_f32_e32 v132, v132
	s_nop 0
	v_mul_f32_e32 v132, v34, v132
	s_cmp_lt_i32 s44, 1
	s_mov_b64 s[42:43], -1
	s_cbranch_scc1 .LBB0_286

.LBB0_832:
	v_mul_f32_e32 v132, 0xbfb8aa3b, v38
	v_exp_f32_e32 v132, v132
	s_nop 0
	v_add_f32_e32 v132, 1.0, v132
	v_rcp_f32_e32 v132, v132
	s_nop 0
	v_mul_f32_e32 v132, v38, v132
	s_cmp_lt_i32 s44, 1
	s_mov_b64 s[42:43], -1
	s_cbranch_scc1 .LBB0_295

.LBB0_836:
	v_mul_f32_e32 v132, 0xbfb8aa3b, v42
	v_exp_f32_e32 v132, v132
	s_nop 0
	v_add_f32_e32 v132, 1.0, v132
	v_rcp_f32_e32 v132, v132
	s_nop 0
	v_mul_f32_e32 v132, v42, v132
	s_cmp_lt_i32 s44, 1
	s_mov_b64 s[42:43], -1
	s_cbranch_scc1 .LBB0_304

.LBB0_840:
	v_mul_f32_e32 v132, 0xbfb8aa3b, v46
	v_exp_f32_e32 v132, v132
	s_nop 0
	v_add_f32_e32 v132, 1.0, v132
	v_rcp_f32_e32 v132, v132
	s_nop 0
	v_mul_f32_e32 v132, v46, v132
	s_cmp_lt_i32 s44, 1
	s_mov_b64 s[42:43], -1
	s_cbranch_scc1 .LBB0_313

.LBB0_844:
	v_mul_f32_e32 v132, 0xbfb8aa3b, v18
	v_exp_f32_e32 v132, v132
	s_nop 0
	v_add_f32_e32 v132, 1.0, v132
	v_rcp_f32_e32 v132, v132
	s_nop 0
	v_mul_f32_e32 v132, v18, v132
	s_cmp_lt_i32 s44, 1
	s_mov_b64 s[42:43], -1
	s_cbranch_scc1 .LBB0_322

.LBB0_848:
	v_mul_f32_e32 v132, 0xbfb8aa3b, v22
	v_exp_f32_e32 v132, v132
	s_nop 0
	v_add_f32_e32 v132, 1.0, v132
	v_rcp_f32_e32 v132, v132
	s_nop 0
	v_mul_f32_e32 v132, v22, v132
	s_cmp_lt_i32 s44, 1
	s_mov_b64 s[42:43], -1
	s_cbranch_scc1 .LBB0_331

.LBB0_852:
	v_mul_f32_e32 v132, 0xbfb8aa3b, v26
	v_exp_f32_e32 v132, v132
	s_nop 0
	v_add_f32_e32 v132, 1.0, v132
	v_rcp_f32_e32 v132, v132
	s_nop 0
	v_mul_f32_e32 v132, v26, v132
	s_cmp_lt_i32 s44, 1
	s_mov_b64 s[42:43], -1
	s_cbranch_scc1 .LBB0_340

.LBB0_856:
	v_mul_f32_e32 v132, 0xbfb8aa3b, v30
	v_exp_f32_e32 v132, v132
	s_nop 0
	v_add_f32_e32 v132, 1.0, v132
	v_rcp_f32_e32 v132, v132
	s_nop 0
	v_mul_f32_e32 v132, v30, v132
	s_cmp_lt_i32 s44, 1
	s_mov_b64 s[42:43], -1
	s_cbranch_scc1 .LBB0_349

.LBB0_860:
	v_mul_f32_e32 v132, 0xbfb8aa3b, v2
	v_exp_f32_e32 v132, v132
	s_nop 0
	v_add_f32_e32 v132, 1.0, v132
	v_rcp_f32_e32 v132, v132
	s_nop 0
	v_mul_f32_e32 v132, v2, v132
	s_cmp_lt_i32 s44, 1
	s_mov_b64 s[42:43], -1
	s_cbranch_scc1 .LBB0_358

.LBB0_864:
	v_mul_f32_e32 v132, 0xbfb8aa3b, v6
	v_exp_f32_e32 v132, v132
	s_nop 0
	v_add_f32_e32 v132, 1.0, v132
	v_rcp_f32_e32 v132, v132
	s_nop 0
	v_mul_f32_e32 v132, v6, v132
	s_cmp_lt_i32 s44, 1
	s_mov_b64 s[42:43], -1
	s_cbranch_scc1 .LBB0_367

.LBB0_868:
	v_mul_f32_e32 v132, 0xbfb8aa3b, v10
	v_exp_f32_e32 v132, v132
	s_nop 0
	v_add_f32_e32 v132, 1.0, v132
	v_rcp_f32_e32 v132, v132
	s_nop 0
	v_mul_f32_e32 v132, v10, v132
	s_cmp_lt_i32 s44, 1
	s_mov_b64 s[42:43], -1
	s_cbranch_scc1 .LBB0_376

.LBB0_872:
	v_mul_f32_e32 v132, 0xbfb8aa3b, v14
	v_exp_f32_e32 v132, v132
	s_nop 0
	v_add_f32_e32 v132, 1.0, v132
	v_rcp_f32_e32 v132, v132
	s_nop 0
	v_mul_f32_e32 v132, v14, v132
	s_cmp_lt_i32 s44, 1
	s_mov_b64 s[42:43], -1
	s_cbranch_scc1 .LBB0_385

.LBB0_989:
	v_mov_b32_e32 v128, v176
	s_waitcnt vmcnt(0) lgkmcnt(0)
	s_barrier
	s_lshl_b32 s64, s69, 8
	v_and_b32_e32 v129, 0xc0, v128
	v_and_b32_e32 v130, 31, v128
	v_lshrrev_b32_e32 v131, 1, v128
	v_lshrrev_b32_e32 v128, 3, v128
	v_and_or_b32 v135, v128, 4, v129
	v_or_b32_e32 v132, s64, v135
	v_and_or_b32 v130, v131, s93, v130
	v_lshl_add_u64 v[128:129], v[132:133], 2, s[6:7]
	v_mul_lo_u32 v141, v130, s0
	global_load_dwordx4 v[128:131], v[128:129], off
	v_lshl_add_u32 v141, v135, 1, v141
	v_or_b32_e32 v134, 32, v132
	s_mov_b32 s3, 0
	s_waitcnt vmcnt(0)
	v_add_f32_e32 v112, v112, v128
	v_add_f32_e32 v113, v113, v129
	v_mul_f32_e32 v112, 0xbfb8aa3b, v112
	v_mul_f32_e32 v113, 0xbfb8aa3b, v113
	v_exp_f32_e32 v112, v112
	v_exp_f32_e32 v113, v113
	v_add_f32_e32 v80, v80, v128
	v_add_f32_e32 v81, v81, v129
	v_mul_f32_e32 v80, 0xbfb8aa3b, v80
	v_pk_add_f32 v[112:113], v[112:113], 1.0 op_sel_hi:[1,0]
	v_mul_f32_e32 v81, 0xbfb8aa3b, v81
	v_exp_f32_e32 v80, v80
	v_exp_f32_e32 v81, v81
	v_add_f32_e32 v48, v48, v128
	v_rcp_f32_e32 v136, v113
	v_pk_add_f32 v[80:81], v[80:81], 1.0 op_sel_hi:[1,0]
	v_add_f32_e32 v49, v49, v129
	v_mul_f32_e32 v48, 0xbfb8aa3b, v48
	v_rcp_f32_e32 v137, v112
	v_add_f32_e32 v112, v114, v130
	v_add_f32_e32 v113, v115, v131
	v_mul_f32_e32 v112, 0xbfb8aa3b, v112
	v_mul_f32_e32 v113, 0xbfb8aa3b, v113
	v_exp_f32_e32 v112, v112
	v_exp_f32_e32 v113, v113
	v_cvt_pk_bf16_f32 v136, v137, v136
	v_mul_f32_e32 v49, 0xbfb8aa3b, v49
	v_exp_f32_e32 v48, v48
	v_pk_add_f32 v[112:113], v[112:113], 1.0 op_sel_hi:[1,0]
	v_exp_f32_e32 v49, v49
	s_nop 0
	v_pk_add_f32 v[48:49], v[48:49], 1.0 op_sel_hi:[1,0]
	v_add_f32_e32 v16, v16, v128
	v_add_f32_e32 v17, v17, v129
	v_rcp_f32_e32 v113, v113
	v_mul_f32_e32 v16, 0xbfb8aa3b, v16
	v_mul_f32_e32 v17, 0xbfb8aa3b, v17
	v_exp_f32_e32 v16, v16
	v_rcp_f32_e32 v112, v112
	s_nop 0
	v_cvt_pk_bf16_f32 v137, v112, v113
	v_or_b32_e32 v112, 8, v132
	v_mov_b32_e32 v113, v133
	v_lshl_add_u64 v[112:113], v[112:113], 2, s[6:7]
	global_load_dwordx4 v[112:115], v[112:113], off
	v_exp_f32_e32 v17, v17
	s_waitcnt vmcnt(0)
	v_add_f32_e32 v116, v116, v112
	v_add_f32_e32 v117, v117, v113
	v_mul_f32_e32 v116, 0xbfb8aa3b, v116
	v_mul_f32_e32 v117, 0xbfb8aa3b, v117
	v_exp_f32_e32 v116, v116
	v_exp_f32_e32 v117, v117
	v_pk_add_f32 v[16:17], v[16:17], 1.0 op_sel_hi:[1,0]
	v_pk_add_f32 v[116:117], v[116:117], 1.0 op_sel_hi:[1,0]
	s_nop 0
	s_nop 0
	v_rcp_f32_e32 v135, v117
	s_nop 0
	v_rcp_f32_e32 v142, v116
	v_add_f32_e32 v116, v118, v114
	v_add_f32_e32 v117, v119, v115
	v_mul_f32_e32 v116, 0xbfb8aa3b, v116
	v_mul_f32_e32 v117, 0xbfb8aa3b, v117
	v_exp_f32_e32 v116, v116
	v_exp_f32_e32 v117, v117
	s_nop 0
	v_pk_add_f32 v[116:117], v[116:117], 1.0 op_sel_hi:[1,0]
	s_nop 0
	s_nop 0
	v_rcp_f32_e32 v117, v117
	s_nop 0
	v_rcp_f32_e32 v118, v116
	v_cvt_pk_bf16_f32 v116, v142, v135
	v_cvt_pk_bf16_f32 v117, v118, v117
	ds_write2_b64 v141, v[136:137], v[116:117] offset1:2
	v_or_b32_e32 v116, 16, v132
	v_mov_b32_e32 v117, v133
	v_lshl_add_u64 v[116:117], v[116:117], 2, s[6:7]
	global_load_dwordx4 v[116:119], v[116:117], off
	s_waitcnt vmcnt(0)
	v_add_f32_e32 v120, v120, v116
	v_add_f32_e32 v121, v121, v117
	v_mul_f32_e32 v120, 0xbfb8aa3b, v120
	v_mul_f32_e32 v121, 0xbfb8aa3b, v121
	v_exp_f32_e32 v120, v120
	v_exp_f32_e32 v121, v121
	s_nop 0
	v_pk_add_f32 v[120:121], v[120:121], 1.0 op_sel_hi:[1,0]
	s_nop 0
	s_nop 0
	v_rcp_f32_e32 v135, v121
	s_nop 0
	v_rcp_f32_e32 v136, v120
	v_add_f32_e32 v120, v122, v118
	v_add_f32_e32 v121, v123, v119
	v_mul_f32_e32 v120, 0xbfb8aa3b, v120
	v_mul_f32_e32 v121, 0xbfb8aa3b, v121
	v_exp_f32_e32 v120, v120
	v_exp_f32_e32 v121, v121
	v_cvt_pk_bf16_f32 v136, v136, v135
	v_pk_add_f32 v[120:121], v[120:121], 1.0 op_sel_hi:[1,0]
	s_nop 0
	s_nop 0
	v_rcp_f32_e32 v121, v121
	s_nop 0
	v_rcp_f32_e32 v120, v120
	s_nop 0
	v_cvt_pk_bf16_f32 v137, v120, v121
	v_or_b32_e32 v120, 24, v132
	v_mov_b32_e32 v121, v133
	v_lshl_add_u64 v[120:121], v[120:121], 2, s[6:7]
	global_load_dwordx4 v[120:123], v[120:121], off
	s_waitcnt vmcnt(0)
	v_add_f32_e32 v124, v124, v120
	v_add_f32_e32 v125, v125, v121
	v_mul_f32_e32 v124, 0xbfb8aa3b, v124
	v_mul_f32_e32 v125, 0xbfb8aa3b, v125
	v_exp_f32_e32 v124, v124
	v_exp_f32_e32 v125, v125
	s_nop 0
	v_pk_add_f32 v[124:125], v[124:125], 1.0 op_sel_hi:[1,0]
	s_nop 0
	s_nop 0
	v_rcp_f32_e32 v135, v125
	s_nop 0
	v_rcp_f32_e32 v142, v124
	v_add_f32_e32 v124, v126, v122
	v_add_f32_e32 v125, v127, v123
	v_mul_f32_e32 v124, 0xbfb8aa3b, v124
	v_mul_f32_e32 v125, 0xbfb8aa3b, v125
	v_exp_f32_e32 v124, v124
	v_exp_f32_e32 v125, v125
	s_nop 0
	v_pk_add_f32 v[124:125], v[124:125], 1.0 op_sel_hi:[1,0]
	s_nop 0
	s_nop 0
	v_rcp_f32_e32 v125, v125
	s_nop 0
	v_rcp_f32_e32 v126, v124
	v_cvt_pk_bf16_f32 v124, v142, v135
	v_cvt_pk_bf16_f32 v125, v126, v125
	v_mov_b32_e32 v135, v133
	ds_write2_b64 v141, v[136:137], v[124:125] offset0:4 offset1:6
	v_lshl_add_u64 v[124:125], v[134:135], 2, s[6:7]
	global_load_dwordx4 v[124:127], v[124:125], off
	s_waitcnt vmcnt(0)
	v_add_f32_e32 v96, v96, v124
	v_add_f32_e32 v97, v97, v125
	v_mul_f32_e32 v96, 0xbfb8aa3b, v96
	v_mul_f32_e32 v97, 0xbfb8aa3b, v97
	v_exp_f32_e32 v96, v96
	v_exp_f32_e32 v97, v97
	v_add_f32_e32 v64, v64, v124
	v_add_f32_e32 v65, v65, v125
	v_mul_f32_e32 v64, 0xbfb8aa3b, v64
	v_pk_add_f32 v[96:97], v[96:97], 1.0 op_sel_hi:[1,0]
	v_mul_f32_e32 v65, 0xbfb8aa3b, v65
	v_exp_f32_e32 v64, v64
	v_exp_f32_e32 v65, v65
	v_add_f32_e32 v32, v32, v124
	v_rcp_f32_e32 v134, v97
	v_pk_add_f32 v[64:65], v[64:65], 1.0 op_sel_hi:[1,0]
	v_add_f32_e32 v33, v33, v125
	v_mul_f32_e32 v32, 0xbfb8aa3b, v32
	v_rcp_f32_e32 v135, v96
	v_add_f32_e32 v96, v98, v126
	v_add_f32_e32 v97, v99, v127
	v_mul_f32_e32 v96, 0xbfb8aa3b, v96
	v_mul_f32_e32 v97, 0xbfb8aa3b, v97
	v_exp_f32_e32 v96, v96
	v_exp_f32_e32 v97, v97
	v_cvt_pk_bf16_f32 v134, v135, v134
	v_mul_f32_e32 v33, 0xbfb8aa3b, v33
	v_exp_f32_e32 v32, v32
	v_pk_add_f32 v[96:97], v[96:97], 1.0 op_sel_hi:[1,0]
	v_exp_f32_e32 v33, v33
	s_nop 0
	v_pk_add_f32 v[32:33], v[32:33], 1.0 op_sel_hi:[1,0]
	v_add_f32_e32 v0, v0, v124
	v_add_f32_e32 v1, v1, v125
	v_rcp_f32_e32 v97, v97
	v_mul_f32_e32 v0, 0xbfb8aa3b, v0
	v_mul_f32_e32 v1, 0xbfb8aa3b, v1
	v_exp_f32_e32 v0, v0
	v_rcp_f32_e32 v96, v96
	s_nop 0
	v_cvt_pk_bf16_f32 v135, v96, v97
	v_or_b32_e32 v96, 40, v132
	v_mov_b32_e32 v97, v133
	v_lshl_add_u64 v[96:97], v[96:97], 2, s[6:7]
	global_load_dwordx4 v[96:99], v[96:97], off
	v_exp_f32_e32 v1, v1
	s_waitcnt vmcnt(0)
	v_add_f32_e32 v100, v100, v96
	v_add_f32_e32 v101, v101, v97
	v_mul_f32_e32 v100, 0xbfb8aa3b, v100
	v_mul_f32_e32 v101, 0xbfb8aa3b, v101
	v_exp_f32_e32 v100, v100
	v_exp_f32_e32 v101, v101
	v_pk_add_f32 v[0:1], v[0:1], 1.0 op_sel_hi:[1,0]
	v_pk_add_f32 v[100:101], v[100:101], 1.0 op_sel_hi:[1,0]
	s_nop 0
	s_nop 0
	v_rcp_f32_e32 v136, v101
	s_nop 0
	v_rcp_f32_e32 v137, v100
	v_add_f32_e32 v100, v102, v98
	v_add_f32_e32 v101, v103, v99
	v_mul_f32_e32 v100, 0xbfb8aa3b, v100
	v_mul_f32_e32 v101, 0xbfb8aa3b, v101
	v_exp_f32_e32 v100, v100
	v_exp_f32_e32 v101, v101
	s_nop 0
	v_pk_add_f32 v[100:101], v[100:101], 1.0 op_sel_hi:[1,0]
	s_nop 0
	s_nop 0
	v_rcp_f32_e32 v101, v101
	s_nop 0
	v_rcp_f32_e32 v102, v100
	v_cvt_pk_bf16_f32 v100, v137, v136
	v_cvt_pk_bf16_f32 v101, v102, v101
	ds_write2_b64 v141, v[134:135], v[100:101] offset0:8 offset1:10
	v_or_b32_e32 v100, 48, v132
	v_mov_b32_e32 v101, v133
	v_lshl_add_u64 v[100:101], v[100:101], 2, s[6:7]
	global_load_dwordx4 v[100:103], v[100:101], off
	v_or_b32_e32 v132, 56, v132
	s_waitcnt vmcnt(0)
	v_add_f32_e32 v104, v104, v100
	v_add_f32_e32 v105, v105, v101
	v_mul_f32_e32 v104, 0xbfb8aa3b, v104
	v_mul_f32_e32 v105, 0xbfb8aa3b, v105
	v_exp_f32_e32 v104, v104
	v_exp_f32_e32 v105, v105
	s_nop 0
	v_pk_add_f32 v[104:105], v[104:105], 1.0 op_sel_hi:[1,0]
	s_nop 0
	s_nop 0
	v_rcp_f32_e32 v134, v105
	s_nop 0
	v_rcp_f32_e32 v135, v104
	v_add_f32_e32 v104, v106, v102
	v_add_f32_e32 v105, v107, v103
	v_mul_f32_e32 v104, 0xbfb8aa3b, v104
	v_mul_f32_e32 v105, 0xbfb8aa3b, v105
	v_exp_f32_e32 v104, v104
	v_exp_f32_e32 v105, v105
	v_cvt_pk_bf16_f32 v134, v135, v134
	v_pk_add_f32 v[104:105], v[104:105], 1.0 op_sel_hi:[1,0]
	s_nop 0
	s_nop 0
	v_rcp_f32_e32 v105, v105
	s_nop 0
	v_rcp_f32_e32 v104, v104
	s_nop 0
	v_cvt_pk_bf16_f32 v135, v104, v105
	v_lshl_add_u64 v[104:105], v[132:133], 2, s[6:7]
	global_load_dwordx4 v[104:107], v[104:105], off
	s_waitcnt vmcnt(0)
	v_add_f32_e32 v108, v108, v104
	v_add_f32_e32 v109, v109, v105
	v_mul_f32_e32 v108, 0xbfb8aa3b, v108
	v_mul_f32_e32 v109, 0xbfb8aa3b, v109
	v_exp_f32_e32 v108, v108
	v_exp_f32_e32 v109, v109
	s_nop 0
	v_pk_add_f32 v[108:109], v[108:109], 1.0 op_sel_hi:[1,0]
	s_nop 0
	s_nop 0
	v_rcp_f32_e32 v132, v109
	s_nop 0
	v_rcp_f32_e32 v136, v108
	v_add_f32_e32 v108, v110, v106
	v_add_f32_e32 v109, v111, v107
	v_mul_f32_e32 v108, 0xbfb8aa3b, v108
	v_mul_f32_e32 v109, 0xbfb8aa3b, v109
	v_exp_f32_e32 v108, v108
	v_exp_f32_e32 v109, v109
	s_nop 0
	v_pk_add_f32 v[108:109], v[108:109], 1.0 op_sel_hi:[1,0]
	s_nop 0
	s_nop 0
	v_rcp_f32_e32 v109, v109
	s_nop 0
	v_rcp_f32_e32 v110, v108
	v_cvt_pk_bf16_f32 v108, v136, v132
	v_cvt_pk_bf16_f32 v109, v110, v109
	ds_write2_b64 v141, v[134:135], v[108:109] offset0:12 offset1:14
	s_nop 0
	v_rcp_f32_e32 v108, v81
	s_nop 0
	v_rcp_f32_e32 v109, v80
	v_add_f32_e32 v80, v82, v130
	v_add_f32_e32 v81, v83, v131
	v_mul_f32_e32 v80, 0xbfb8aa3b, v80
	v_mul_f32_e32 v81, 0xbfb8aa3b, v81
	v_exp_f32_e32 v80, v80
	v_exp_f32_e32 v81, v81
	s_nop 0
	v_pk_add_f32 v[80:81], v[80:81], 1.0 op_sel_hi:[1,0]
	s_nop 0
	s_nop 0
	v_rcp_f32_e32 v81, v81
	s_nop 0
	v_rcp_f32_e32 v80, v80
	s_nop 0
	v_cvt_pk_bf16_f32 v83, v80, v81
	v_add_f32_e32 v80, v84, v112
	v_add_f32_e32 v81, v85, v113
	v_mul_f32_e32 v80, 0xbfb8aa3b, v80
	v_mul_f32_e32 v81, 0xbfb8aa3b, v81
	v_exp_f32_e32 v80, v80
	v_exp_f32_e32 v81, v81
	v_cvt_pk_bf16_f32 v82, v109, v108
	v_pk_add_f32 v[80:81], v[80:81], 1.0 op_sel_hi:[1,0]
	s_nop 0
	s_nop 0
	v_rcp_f32_e32 v84, v81
	s_nop 0
	v_rcp_f32_e32 v85, v80
	v_add_f32_e32 v80, v86, v114
	v_add_f32_e32 v81, v87, v115
	v_mul_f32_e32 v80, 0xbfb8aa3b, v80
	v_mul_f32_e32 v81, 0xbfb8aa3b, v81
	v_exp_f32_e32 v80, v80
	v_exp_f32_e32 v81, v81
	v_cvt_pk_bf16_f32 v84, v85, v84
	v_pk_add_f32 v[80:81], v[80:81], 1.0 op_sel_hi:[1,0]
	s_nop 0
	s_nop 0
	v_rcp_f32_e32 v81, v81
	s_nop 0
	v_rcp_f32_e32 v80, v80
	s_nop 0
	v_cvt_pk_bf16_f32 v85, v80, v81
	v_add_f32_e32 v81, v88, v116
	v_add_u32_e32 v80, 0x4000, v141
	v_mul_f32_e32 v81, 0xbfb8aa3b, v81
	ds_write2_b64 v80, v[82:83], v[84:85] offset0:64 offset1:66
	v_exp_f32_e32 v82, v81
	v_add_f32_e32 v81, v89, v117
	v_mul_f32_e32 v81, 0xbfb8aa3b, v81
	v_exp_f32_e32 v83, v81
	s_nop 0
	v_pk_add_f32 v[82:83], v[82:83], 1.0 op_sel_hi:[1,0]
	s_nop 0
	s_nop 0
	v_rcp_f32_e32 v81, v83
	s_nop 0
	v_rcp_f32_e32 v84, v82
	v_add_f32_e32 v82, v90, v118
	v_add_f32_e32 v83, v91, v119
	v_mul_f32_e32 v82, 0xbfb8aa3b, v82
	v_mul_f32_e32 v83, 0xbfb8aa3b, v83
	v_exp_f32_e32 v82, v82
	v_exp_f32_e32 v83, v83
	s_nop 0
	v_pk_add_f32 v[82:83], v[82:83], 1.0 op_sel_hi:[1,0]
	s_nop 0
	s_nop 0
	v_rcp_f32_e32 v83, v83
	s_nop 0
	v_rcp_f32_e32 v85, v82
	v_cvt_pk_bf16_f32 v82, v84, v81
	v_add_f32_e32 v81, v92, v120
	v_mul_f32_e32 v81, 0xbfb8aa3b, v81
	v_exp_f32_e32 v84, v81
	v_add_f32_e32 v81, v93, v121
	v_mul_f32_e32 v81, 0xbfb8aa3b, v81
	v_cvt_pk_bf16_f32 v83, v85, v83
	v_exp_f32_e32 v85, v81
	s_nop 0
	v_pk_add_f32 v[84:85], v[84:85], 1.0 op_sel_hi:[1,0]
	s_nop 0
	s_nop 0
	v_rcp_f32_e32 v81, v85
	s_nop 0
	v_rcp_f32_e32 v86, v84
	v_add_f32_e32 v84, v94, v122
	v_add_f32_e32 v85, v95, v123
	v_mul_f32_e32 v84, 0xbfb8aa3b, v84
	v_mul_f32_e32 v85, 0xbfb8aa3b, v85
	v_exp_f32_e32 v84, v84
	v_exp_f32_e32 v85, v85
	s_nop 0
	v_pk_add_f32 v[84:85], v[84:85], 1.0 op_sel_hi:[1,0]
	s_nop 0
	s_nop 0
	v_rcp_f32_e32 v85, v85
	s_nop 0
	v_rcp_f32_e32 v87, v84
	v_cvt_pk_bf16_f32 v84, v86, v81
	v_cvt_pk_bf16_f32 v85, v87, v85
	ds_write2_b64 v80, v[82:83], v[84:85] offset0:68 offset1:70
	s_nop 0
	v_rcp_f32_e32 v81, v65
	s_nop 0
	v_rcp_f32_e32 v82, v64
	v_add_f32_e32 v64, v66, v126
	v_add_f32_e32 v65, v67, v127
	v_mul_f32_e32 v64, 0xbfb8aa3b, v64
	v_mul_f32_e32 v65, 0xbfb8aa3b, v65
	v_exp_f32_e32 v64, v64
	v_exp_f32_e32 v65, v65
	s_nop 0
	v_pk_add_f32 v[64:65], v[64:65], 1.0 op_sel_hi:[1,0]
	s_nop 0
	s_nop 0
	v_rcp_f32_e32 v65, v65
	s_nop 0
	v_rcp_f32_e32 v66, v64
	s_nop 0
	v_cvt_pk_bf16_f32 v65, v66, v65
	v_add_f32_e32 v66, v68, v96
	v_add_f32_e32 v67, v69, v97
	v_mul_f32_e32 v66, 0xbfb8aa3b, v66
	v_mul_f32_e32 v67, 0xbfb8aa3b, v67
	v_exp_f32_e32 v66, v66
	v_exp_f32_e32 v67, v67
	v_cvt_pk_bf16_f32 v64, v82, v81
	v_pk_add_f32 v[66:67], v[66:67], 1.0 op_sel_hi:[1,0]
	s_nop 0
	s_nop 0
	v_rcp_f32_e32 v68, v67
	s_nop 0
	v_rcp_f32_e32 v69, v66
	v_add_f32_e32 v66, v70, v98
	v_add_f32_e32 v67, v71, v99
	v_mul_f32_e32 v66, 0xbfb8aa3b, v66
	v_mul_f32_e32 v67, 0xbfb8aa3b, v67
	v_exp_f32_e32 v66, v66
	v_exp_f32_e32 v67, v67
	s_nop 0
	v_pk_add_f32 v[66:67], v[66:67], 1.0 op_sel_hi:[1,0]
	s_nop 0
	s_nop 0
	v_rcp_f32_e32 v67, v67
	s_nop 0
	v_rcp_f32_e32 v70, v66
	v_cvt_pk_bf16_f32 v66, v69, v68
	v_cvt_pk_bf16_f32 v67, v70, v67
	ds_write2_b64 v80, v[64:65], v[66:67] offset0:72 offset1:74
	v_add_f32_e32 v64, v72, v100
	v_add_f32_e32 v65, v73, v101
	v_mul_f32_e32 v64, 0xbfb8aa3b, v64
	v_mul_f32_e32 v65, 0xbfb8aa3b, v65
	v_exp_f32_e32 v64, v64
	v_exp_f32_e32 v65, v65
	s_nop 0
	v_pk_add_f32 v[64:65], v[64:65], 1.0 op_sel_hi:[1,0]
	s_nop 0
	s_nop 0
	v_rcp_f32_e32 v66, v65
	s_nop 0
	v_rcp_f32_e32 v67, v64
	v_add_f32_e32 v64, v74, v102
	v_add_f32_e32 v65, v75, v103
	v_mul_f32_e32 v64, 0xbfb8aa3b, v64
	v_mul_f32_e32 v65, 0xbfb8aa3b, v65
	v_exp_f32_e32 v64, v64
	v_exp_f32_e32 v65, v65
	s_nop 0
	v_pk_add_f32 v[64:65], v[64:65], 1.0 op_sel_hi:[1,0]
	s_nop 0
	s_nop 0
	v_rcp_f32_e32 v65, v65
	s_nop 0
	v_rcp_f32_e32 v68, v64
	v_cvt_pk_bf16_f32 v64, v67, v66
	v_add_f32_e32 v66, v76, v104
	v_add_f32_e32 v67, v77, v105
	v_mul_f32_e32 v66, 0xbfb8aa3b, v66
	v_mul_f32_e32 v67, 0xbfb8aa3b, v67
	v_exp_f32_e32 v66, v66
	v_exp_f32_e32 v67, v67
	v_cvt_pk_bf16_f32 v65, v68, v65
	v_pk_add_f32 v[66:67], v[66:67], 1.0 op_sel_hi:[1,0]
	s_nop 0
	s_nop 0
	v_rcp_f32_e32 v68, v67
	s_nop 0
	v_rcp_f32_e32 v69, v66
	v_add_f32_e32 v66, v78, v106
	v_add_f32_e32 v67, v79, v107
	v_mul_f32_e32 v66, 0xbfb8aa3b, v66
	v_mul_f32_e32 v67, 0xbfb8aa3b, v67
	v_exp_f32_e32 v66, v66
	v_exp_f32_e32 v67, v67
	s_nop 0
	v_pk_add_f32 v[66:67], v[66:67], 1.0 op_sel_hi:[1,0]
	s_nop 0
	s_nop 0
	v_rcp_f32_e32 v67, v67
	s_nop 0
	v_rcp_f32_e32 v70, v66
	v_cvt_pk_bf16_f32 v66, v69, v68
	v_cvt_pk_bf16_f32 v67, v70, v67
	ds_write2_b64 v80, v[64:65], v[66:67] offset0:76 offset1:78
	s_nop 0
	v_rcp_f32_e32 v64, v49
	s_nop 0
	v_rcp_f32_e32 v65, v48
	v_add_f32_e32 v48, v50, v130
	v_add_f32_e32 v49, v51, v131
	v_mul_f32_e32 v48, 0xbfb8aa3b, v48
	v_mul_f32_e32 v49, 0xbfb8aa3b, v49
	v_exp_f32_e32 v48, v48
	v_exp_f32_e32 v49, v49
	s_nop 0
	v_pk_add_f32 v[48:49], v[48:49], 1.0 op_sel_hi:[1,0]
	s_nop 0
	s_nop 0
	v_rcp_f32_e32 v49, v49
	s_nop 0
	v_rcp_f32_e32 v48, v48
	s_nop 0
	v_cvt_pk_bf16_f32 v51, v48, v49
	v_add_f32_e32 v48, v52, v112
	v_add_f32_e32 v49, v53, v113
	v_mul_f32_e32 v48, 0xbfb8aa3b, v48
	v_mul_f32_e32 v49, 0xbfb8aa3b, v49
	v_exp_f32_e32 v48, v48
	v_exp_f32_e32 v49, v49
	v_cvt_pk_bf16_f32 v50, v65, v64
	v_pk_add_f32 v[48:49], v[48:49], 1.0 op_sel_hi:[1,0]
	s_nop 0
	s_nop 0
	v_rcp_f32_e32 v52, v49
	s_nop 0
	v_rcp_f32_e32 v53, v48
	v_add_f32_e32 v48, v54, v114
	v_add_f32_e32 v49, v55, v115
	v_mul_f32_e32 v48, 0xbfb8aa3b, v48
	v_mul_f32_e32 v49, 0xbfb8aa3b, v49
	v_exp_f32_e32 v48, v48
	v_exp_f32_e32 v49, v49
	v_cvt_pk_bf16_f32 v52, v53, v52
	v_pk_add_f32 v[48:49], v[48:49], 1.0 op_sel_hi:[1,0]
	s_nop 0
	s_nop 0
	v_rcp_f32_e32 v49, v49
	s_nop 0
	v_rcp_f32_e32 v48, v48
	s_nop 0
	v_cvt_pk_bf16_f32 v53, v48, v49
	v_add_f32_e32 v49, v56, v116
	v_add_u32_e32 v48, 0x8000, v141
	v_mul_f32_e32 v49, 0xbfb8aa3b, v49
	ds_write2_b64 v48, v[50:51], v[52:53] offset0:128 offset1:130
	v_exp_f32_e32 v50, v49
	v_add_f32_e32 v49, v57, v117
	v_mul_f32_e32 v49, 0xbfb8aa3b, v49
	v_exp_f32_e32 v51, v49
	s_nop 0
	v_pk_add_f32 v[50:51], v[50:51], 1.0 op_sel_hi:[1,0]
	s_nop 0
	s_nop 0
	v_rcp_f32_e32 v49, v51
	s_nop 0
	v_rcp_f32_e32 v52, v50
	v_add_f32_e32 v50, v58, v118
	v_add_f32_e32 v51, v59, v119
	v_mul_f32_e32 v50, 0xbfb8aa3b, v50
	v_mul_f32_e32 v51, 0xbfb8aa3b, v51
	v_exp_f32_e32 v50, v50
	v_exp_f32_e32 v51, v51
	s_nop 0
	v_pk_add_f32 v[50:51], v[50:51], 1.0 op_sel_hi:[1,0]
	s_nop 0
	s_nop 0
	v_rcp_f32_e32 v51, v51
	s_nop 0
	v_rcp_f32_e32 v53, v50
	v_cvt_pk_bf16_f32 v50, v52, v49
	v_add_f32_e32 v49, v60, v120
	v_mul_f32_e32 v49, 0xbfb8aa3b, v49
	v_exp_f32_e32 v52, v49
	v_add_f32_e32 v49, v61, v121
	v_mul_f32_e32 v49, 0xbfb8aa3b, v49
	v_cvt_pk_bf16_f32 v51, v53, v51
	v_exp_f32_e32 v53, v49
	s_nop 0
	v_pk_add_f32 v[52:53], v[52:53], 1.0 op_sel_hi:[1,0]
	s_nop 0
	s_nop 0
	v_rcp_f32_e32 v49, v53
	s_nop 0
	v_rcp_f32_e32 v54, v52
	v_add_f32_e32 v52, v62, v122
	v_add_f32_e32 v53, v63, v123
	v_mul_f32_e32 v52, 0xbfb8aa3b, v52
	v_mul_f32_e32 v53, 0xbfb8aa3b, v53
	v_exp_f32_e32 v52, v52
	v_exp_f32_e32 v53, v53
	s_nop 0
	v_pk_add_f32 v[52:53], v[52:53], 1.0 op_sel_hi:[1,0]
	s_nop 0
	s_nop 0
	v_rcp_f32_e32 v53, v53
	s_nop 0
	v_rcp_f32_e32 v55, v52
	v_cvt_pk_bf16_f32 v52, v54, v49
	v_cvt_pk_bf16_f32 v53, v55, v53
	ds_write2_b64 v48, v[50:51], v[52:53] offset0:132 offset1:134
	s_nop 0
	v_rcp_f32_e32 v49, v33
	s_nop 0
	v_rcp_f32_e32 v50, v32
	v_add_f32_e32 v32, v34, v126
	v_add_f32_e32 v33, v35, v127
	v_mul_f32_e32 v32, 0xbfb8aa3b, v32
	v_mul_f32_e32 v33, 0xbfb8aa3b, v33
	v_exp_f32_e32 v32, v32
	v_exp_f32_e32 v33, v33
	s_nop 0
	v_pk_add_f32 v[32:33], v[32:33], 1.0 op_sel_hi:[1,0]
	s_nop 0
	s_nop 0
	v_rcp_f32_e32 v33, v33
	s_nop 0
	v_rcp_f32_e32 v34, v32
	s_nop 0
	v_cvt_pk_bf16_f32 v33, v34, v33
	v_add_f32_e32 v34, v36, v96
	v_add_f32_e32 v35, v37, v97
	v_mul_f32_e32 v34, 0xbfb8aa3b, v34
	v_mul_f32_e32 v35, 0xbfb8aa3b, v35
	v_exp_f32_e32 v34, v34
	v_exp_f32_e32 v35, v35
	v_cvt_pk_bf16_f32 v32, v50, v49
	v_pk_add_f32 v[34:35], v[34:35], 1.0 op_sel_hi:[1,0]
	s_nop 0
	s_nop 0
	v_rcp_f32_e32 v36, v35
	s_nop 0
	v_rcp_f32_e32 v37, v34
	v_add_f32_e32 v34, v38, v98
	v_add_f32_e32 v35, v39, v99
	v_mul_f32_e32 v34, 0xbfb8aa3b, v34
	v_mul_f32_e32 v35, 0xbfb8aa3b, v35
	v_exp_f32_e32 v34, v34
	v_exp_f32_e32 v35, v35
	s_nop 0
	v_pk_add_f32 v[34:35], v[34:35], 1.0 op_sel_hi:[1,0]
	s_nop 0
	s_nop 0
	v_rcp_f32_e32 v35, v35
	s_nop 0
	v_rcp_f32_e32 v38, v34
	v_cvt_pk_bf16_f32 v34, v37, v36
	v_cvt_pk_bf16_f32 v35, v38, v35
	ds_write2_b64 v48, v[32:33], v[34:35] offset0:136 offset1:138
	v_add_f32_e32 v32, v40, v100
	v_add_f32_e32 v33, v41, v101
	v_mul_f32_e32 v32, 0xbfb8aa3b, v32
	v_mul_f32_e32 v33, 0xbfb8aa3b, v33
	v_exp_f32_e32 v32, v32
	v_exp_f32_e32 v33, v33
	s_nop 0
	v_pk_add_f32 v[32:33], v[32:33], 1.0 op_sel_hi:[1,0]
	s_nop 0
	s_nop 0
	v_rcp_f32_e32 v34, v33
	s_nop 0
	v_rcp_f32_e32 v35, v32
	v_add_f32_e32 v32, v42, v102
	v_add_f32_e32 v33, v43, v103
	v_mul_f32_e32 v32, 0xbfb8aa3b, v32
	v_mul_f32_e32 v33, 0xbfb8aa3b, v33
	v_exp_f32_e32 v32, v32
	v_exp_f32_e32 v33, v33
	s_nop 0
	v_pk_add_f32 v[32:33], v[32:33], 1.0 op_sel_hi:[1,0]
	s_nop 0
	s_nop 0
	v_rcp_f32_e32 v33, v33
	s_nop 0
	v_rcp_f32_e32 v36, v32
	v_cvt_pk_bf16_f32 v32, v35, v34
	v_add_f32_e32 v34, v44, v104
	v_add_f32_e32 v35, v45, v105
	v_mul_f32_e32 v34, 0xbfb8aa3b, v34
	v_mul_f32_e32 v35, 0xbfb8aa3b, v35
	v_exp_f32_e32 v34, v34
	v_exp_f32_e32 v35, v35
	v_cvt_pk_bf16_f32 v33, v36, v33
	v_pk_add_f32 v[34:35], v[34:35], 1.0 op_sel_hi:[1,0]
	s_nop 0
	s_nop 0
	v_rcp_f32_e32 v36, v35
	s_nop 0
	v_rcp_f32_e32 v37, v34
	v_add_f32_e32 v34, v46, v106
	v_add_f32_e32 v35, v47, v107
	v_mul_f32_e32 v34, 0xbfb8aa3b, v34
	v_mul_f32_e32 v35, 0xbfb8aa3b, v35
	v_exp_f32_e32 v34, v34
	v_exp_f32_e32 v35, v35
	s_nop 0
	v_pk_add_f32 v[34:35], v[34:35], 1.0 op_sel_hi:[1,0]
	s_nop 0
	s_nop 0
	v_rcp_f32_e32 v35, v35
	s_nop 0
	v_rcp_f32_e32 v38, v34
	v_cvt_pk_bf16_f32 v34, v37, v36
	v_cvt_pk_bf16_f32 v35, v38, v35
	ds_write2_b64 v48, v[32:33], v[34:35] offset0:140 offset1:142
	s_nop 0
	v_rcp_f32_e32 v32, v17
	s_nop 0
	v_rcp_f32_e32 v33, v16
	v_add_f32_e32 v16, v18, v130
	v_add_f32_e32 v17, v19, v131
	v_mul_f32_e32 v16, 0xbfb8aa3b, v16
	v_mul_f32_e32 v17, 0xbfb8aa3b, v17
	v_exp_f32_e32 v16, v16
	v_exp_f32_e32 v17, v17
	s_nop 0
	v_pk_add_f32 v[16:17], v[16:17], 1.0 op_sel_hi:[1,0]
	s_nop 0
	s_nop 0
	v_rcp_f32_e32 v17, v17
	s_nop 0
	v_rcp_f32_e32 v16, v16
	s_nop 0
	v_cvt_pk_bf16_f32 v19, v16, v17
	v_add_f32_e32 v16, v20, v112
	v_add_f32_e32 v17, v21, v113
	v_mul_f32_e32 v16, 0xbfb8aa3b, v16
	v_mul_f32_e32 v17, 0xbfb8aa3b, v17
	v_exp_f32_e32 v16, v16
	v_exp_f32_e32 v17, v17
	v_cvt_pk_bf16_f32 v18, v33, v32
	v_pk_add_f32 v[16:17], v[16:17], 1.0 op_sel_hi:[1,0]
	s_nop 0
	s_nop 0
	v_rcp_f32_e32 v20, v17
	s_nop 0
	v_rcp_f32_e32 v21, v16
	v_add_f32_e32 v16, v22, v114
	v_add_f32_e32 v17, v23, v115
	v_mul_f32_e32 v16, 0xbfb8aa3b, v16
	v_mul_f32_e32 v17, 0xbfb8aa3b, v17
	v_exp_f32_e32 v16, v16
	v_exp_f32_e32 v17, v17
	v_cvt_pk_bf16_f32 v20, v21, v20
	v_pk_add_f32 v[16:17], v[16:17], 1.0 op_sel_hi:[1,0]
	s_nop 0
	s_nop 0
	v_rcp_f32_e32 v17, v17
	s_nop 0
	v_rcp_f32_e32 v16, v16
	s_nop 0
	v_cvt_pk_bf16_f32 v21, v16, v17
	v_add_f32_e32 v17, v24, v116
	v_add_u32_e32 v16, 0xc000, v141
	v_mul_f32_e32 v17, 0xbfb8aa3b, v17
	ds_write2_b64 v16, v[18:19], v[20:21] offset0:192 offset1:194
	v_exp_f32_e32 v18, v17
	v_add_f32_e32 v17, v25, v117
	v_mul_f32_e32 v17, 0xbfb8aa3b, v17
	v_exp_f32_e32 v19, v17
	s_nop 0
	v_pk_add_f32 v[18:19], v[18:19], 1.0 op_sel_hi:[1,0]
	s_nop 0
	s_nop 0
	v_rcp_f32_e32 v17, v19
	s_nop 0
	v_rcp_f32_e32 v20, v18
	v_add_f32_e32 v18, v26, v118
	v_add_f32_e32 v19, v27, v119
	v_mul_f32_e32 v18, 0xbfb8aa3b, v18
	v_mul_f32_e32 v19, 0xbfb8aa3b, v19
	v_exp_f32_e32 v18, v18
	v_exp_f32_e32 v19, v19
	s_nop 0
	v_pk_add_f32 v[18:19], v[18:19], 1.0 op_sel_hi:[1,0]
	s_nop 0
	s_nop 0
	v_rcp_f32_e32 v19, v19
	s_nop 0
	v_rcp_f32_e32 v21, v18
	v_cvt_pk_bf16_f32 v18, v20, v17
	v_add_f32_e32 v17, v28, v120
	v_mul_f32_e32 v17, 0xbfb8aa3b, v17
	v_exp_f32_e32 v20, v17
	v_add_f32_e32 v17, v29, v121
	v_mul_f32_e32 v17, 0xbfb8aa3b, v17
	v_cvt_pk_bf16_f32 v19, v21, v19
	v_exp_f32_e32 v21, v17
	s_nop 0
	v_pk_add_f32 v[20:21], v[20:21], 1.0 op_sel_hi:[1,0]
	s_nop 0
	s_nop 0
	v_rcp_f32_e32 v17, v21
	s_nop 0
	v_rcp_f32_e32 v22, v20
	v_add_f32_e32 v20, v30, v122
	v_add_f32_e32 v21, v31, v123
	v_mul_f32_e32 v20, 0xbfb8aa3b, v20
	v_mul_f32_e32 v21, 0xbfb8aa3b, v21
	v_exp_f32_e32 v20, v20
	v_exp_f32_e32 v21, v21
	s_nop 0
	v_pk_add_f32 v[20:21], v[20:21], 1.0 op_sel_hi:[1,0]
	s_nop 0
	s_nop 0
	v_rcp_f32_e32 v21, v21
	s_nop 0
	v_rcp_f32_e32 v23, v20
	v_cvt_pk_bf16_f32 v20, v22, v17
	v_cvt_pk_bf16_f32 v21, v23, v21
	ds_write2_b64 v16, v[18:19], v[20:21] offset0:196 offset1:198
	s_nop 0
	v_rcp_f32_e32 v17, v1
	s_nop 0
	v_rcp_f32_e32 v18, v0
	v_add_f32_e32 v0, v2, v126
	v_add_f32_e32 v1, v3, v127
	v_mul_f32_e32 v0, 0xbfb8aa3b, v0
	v_mul_f32_e32 v1, 0xbfb8aa3b, v1
	v_exp_f32_e32 v0, v0
	v_exp_f32_e32 v1, v1
	s_nop 0
	v_pk_add_f32 v[0:1], v[0:1], 1.0 op_sel_hi:[1,0]
	s_nop 0
	s_nop 0
	v_rcp_f32_e32 v1, v1
	s_nop 0
	v_rcp_f32_e32 v2, v0
	s_nop 0
	v_cvt_pk_bf16_f32 v1, v2, v1
	v_add_f32_e32 v2, v4, v96
	v_add_f32_e32 v3, v5, v97
	v_mul_f32_e32 v2, 0xbfb8aa3b, v2
	v_mul_f32_e32 v3, 0xbfb8aa3b, v3
	v_exp_f32_e32 v2, v2
	v_exp_f32_e32 v3, v3
	v_cvt_pk_bf16_f32 v0, v18, v17
	v_pk_add_f32 v[2:3], v[2:3], 1.0 op_sel_hi:[1,0]
	s_nop 0
	s_nop 0
	v_rcp_f32_e32 v4, v3
	s_nop 0
	v_rcp_f32_e32 v5, v2
	v_add_f32_e32 v2, v6, v98
	v_add_f32_e32 v3, v7, v99
	v_mul_f32_e32 v2, 0xbfb8aa3b, v2
	v_mul_f32_e32 v3, 0xbfb8aa3b, v3
	v_exp_f32_e32 v2, v2
	v_exp_f32_e32 v3, v3
	s_nop 0
	v_pk_add_f32 v[2:3], v[2:3], 1.0 op_sel_hi:[1,0]
	s_nop 0
	s_nop 0
	v_rcp_f32_e32 v3, v3
	s_nop 0
	v_rcp_f32_e32 v6, v2
	v_cvt_pk_bf16_f32 v2, v5, v4
	v_cvt_pk_bf16_f32 v3, v6, v3
	ds_write2_b64 v16, v[0:1], v[2:3] offset0:200 offset1:202
	v_add_f32_e32 v0, v8, v100
	v_add_f32_e32 v1, v9, v101
	v_mul_f32_e32 v0, 0xbfb8aa3b, v0
	v_mul_f32_e32 v1, 0xbfb8aa3b, v1
	v_exp_f32_e32 v0, v0
	v_exp_f32_e32 v1, v1
	s_nop 0
	v_pk_add_f32 v[0:1], v[0:1], 1.0 op_sel_hi:[1,0]
	s_nop 0
	s_nop 0
	v_rcp_f32_e32 v2, v1
	s_nop 0
	v_rcp_f32_e32 v3, v0
	v_add_f32_e32 v0, v10, v102
	v_add_f32_e32 v1, v11, v103
	v_mul_f32_e32 v0, 0xbfb8aa3b, v0
	v_mul_f32_e32 v1, 0xbfb8aa3b, v1
	v_exp_f32_e32 v0, v0
	v_exp_f32_e32 v1, v1
	s_nop 0
	v_pk_add_f32 v[0:1], v[0:1], 1.0 op_sel_hi:[1,0]
	s_nop 0
	s_nop 0
	v_rcp_f32_e32 v1, v1
	s_nop 0
	v_rcp_f32_e32 v4, v0
	v_cvt_pk_bf16_f32 v0, v3, v2
	v_add_f32_e32 v2, v12, v104
	v_add_f32_e32 v3, v13, v105
	v_mul_f32_e32 v2, 0xbfb8aa3b, v2
	v_mul_f32_e32 v3, 0xbfb8aa3b, v3
	v_exp_f32_e32 v2, v2
	v_exp_f32_e32 v3, v3
	v_cvt_pk_bf16_f32 v1, v4, v1
	v_pk_add_f32 v[2:3], v[2:3], 1.0 op_sel_hi:[1,0]
	s_nop 0
	s_nop 0
	v_rcp_f32_e32 v4, v3
	s_nop 0
	v_rcp_f32_e32 v5, v2
	v_add_f32_e32 v2, v14, v106
	v_add_f32_e32 v3, v15, v107
	v_mul_f32_e32 v2, 0xbfb8aa3b, v2
	v_mul_f32_e32 v3, 0xbfb8aa3b, v3
	v_exp_f32_e32 v2, v2
	v_exp_f32_e32 v3, v3
	s_nop 0
	v_pk_add_f32 v[2:3], v[2:3], 1.0 op_sel_hi:[1,0]
	s_nop 0
	s_nop 0
	v_rcp_f32_e32 v3, v3
	s_nop 0
	v_rcp_f32_e32 v6, v2
	v_cvt_pk_bf16_f32 v2, v5, v4
	v_cvt_pk_bf16_f32 v3, v6, v3
	ds_write2_b64 v16, v[0:1], v[2:3] offset0:204 offset1:206
	v_mov_b32_e32 v1, v176
	s_waitcnt lgkmcnt(0)
	s_barrier
	s_nop 0
	v_lshlrev_b32_e32 v0, 3, v1
	v_and_b32_e32 v0, 0xf8, v0
	v_or_b32_e32 v2, s64, v0
	v_lshlrev_b32_e32 v132, 1, v2
	v_lshlrev_b32_e32 v0, 1, v0
	v_lshl_add_u64 v[2:3], s[54:55], 0, v[132:133]

.LBB0_1009:
	v_mov_b32_e32 v128, v176
	s_waitcnt vmcnt(0) lgkmcnt(0)
	s_barrier
	s_lshl_b32 s68, s73, 8
	v_and_b32_e32 v129, 0xc0, v128
	v_and_b32_e32 v130, 31, v128
	v_lshrrev_b32_e32 v131, 1, v128
	v_lshrrev_b32_e32 v128, 3, v128
	v_and_or_b32 v141, v128, 4, v129
	v_or_b32_e32 v132, s68, v141
	v_and_or_b32 v130, v131, s93, v130
	v_lshl_add_u64 v[134:135], v[132:133], 2, s[80:81]
	v_mul_lo_u32 v142, v130, s0
	global_load_dwordx4 v[128:131], v[134:135], off
	s_mov_b32 s3, 0
	s_waitcnt vmcnt(0)
	v_add_f32_e32 v112, v112, v128
	v_add_f32_e32 v113, v113, v129
	v_mul_f32_e32 v112, 0xbfb8aa3b, v112
	v_mul_f32_e32 v113, 0xbfb8aa3b, v113
	v_exp_f32_e32 v112, v112
	v_exp_f32_e32 v113, v113
	v_add_f32_e32 v80, v80, v128
	v_add_f32_e32 v81, v81, v129
	v_mul_f32_e32 v80, 0xbfb8aa3b, v80
	v_pk_add_f32 v[112:113], v[112:113], 1.0 op_sel_hi:[1,0]
	v_mul_f32_e32 v81, 0xbfb8aa3b, v81
	v_exp_f32_e32 v80, v80
	v_exp_f32_e32 v81, v81
	v_add_f32_e32 v48, v48, v128
	v_rcp_f32_e32 v132, v113
	v_pk_add_f32 v[80:81], v[80:81], 1.0 op_sel_hi:[1,0]
	v_add_f32_e32 v49, v49, v129
	v_mul_f32_e32 v48, 0xbfb8aa3b, v48
	v_rcp_f32_e32 v136, v112
	v_add_f32_e32 v112, v114, v130
	v_add_f32_e32 v113, v115, v131
	v_mul_f32_e32 v112, 0xbfb8aa3b, v112
	v_mul_f32_e32 v113, 0xbfb8aa3b, v113
	v_exp_f32_e32 v112, v112
	v_exp_f32_e32 v113, v113
	v_cvt_pk_bf16_f32 v136, v136, v132
	v_lshl_add_u32 v132, v141, 1, v142
	v_mul_f32_e32 v49, 0xbfb8aa3b, v49
	v_pk_add_f32 v[112:113], v[112:113], 1.0 op_sel_hi:[1,0]
	v_exp_f32_e32 v48, v48
	v_exp_f32_e32 v49, v49
	v_add_f32_e32 v16, v16, v128
	v_add_f32_e32 v17, v17, v129
	v_rcp_f32_e32 v113, v113
	v_pk_add_f32 v[48:49], v[48:49], 1.0 op_sel_hi:[1,0]
	v_mul_f32_e32 v16, 0xbfb8aa3b, v16
	v_mul_f32_e32 v17, 0xbfb8aa3b, v17
	v_rcp_f32_e32 v112, v112
	s_nop 0
	v_cvt_pk_bf16_f32 v137, v112, v113
	global_load_dwordx4 v[112:115], v[134:135], off offset:32
	v_exp_f32_e32 v16, v16
	v_exp_f32_e32 v17, v17
	s_waitcnt vmcnt(0)
	v_add_f32_e32 v116, v116, v112
	v_add_f32_e32 v117, v117, v113
	v_mul_f32_e32 v116, 0xbfb8aa3b, v116
	v_mul_f32_e32 v117, 0xbfb8aa3b, v117
	v_exp_f32_e32 v116, v116
	v_exp_f32_e32 v117, v117
	v_pk_add_f32 v[16:17], v[16:17], 1.0 op_sel_hi:[1,0]
	v_pk_add_f32 v[116:117], v[116:117], 1.0 op_sel_hi:[1,0]
	s_nop 0
	s_nop 0
	v_rcp_f32_e32 v141, v117
	s_nop 0
	v_rcp_f32_e32 v142, v116
	v_add_f32_e32 v116, v118, v114
	v_add_f32_e32 v117, v119, v115
	v_mul_f32_e32 v116, 0xbfb8aa3b, v116
	v_mul_f32_e32 v117, 0xbfb8aa3b, v117
	v_exp_f32_e32 v116, v116
	v_exp_f32_e32 v117, v117
	s_nop 0
	v_pk_add_f32 v[116:117], v[116:117], 1.0 op_sel_hi:[1,0]
	s_nop 0
	s_nop 0
	v_rcp_f32_e32 v117, v117
	s_nop 0
	v_rcp_f32_e32 v118, v116
	v_cvt_pk_bf16_f32 v116, v142, v141
	v_cvt_pk_bf16_f32 v117, v118, v117
	ds_write2_b64 v132, v[136:137], v[116:117] offset1:2
	global_load_dwordx4 v[116:119], v[134:135], off offset:64
	s_waitcnt vmcnt(0)
	v_add_f32_e32 v120, v120, v116
	v_add_f32_e32 v121, v121, v117
	v_mul_f32_e32 v120, 0xbfb8aa3b, v120
	v_mul_f32_e32 v121, 0xbfb8aa3b, v121
	v_exp_f32_e32 v120, v120
	v_exp_f32_e32 v121, v121
	s_nop 0
	v_pk_add_f32 v[120:121], v[120:121], 1.0 op_sel_hi:[1,0]
	s_nop 0
	s_nop 0
	v_rcp_f32_e32 v136, v121
	s_nop 0
	v_rcp_f32_e32 v137, v120
	v_add_f32_e32 v120, v122, v118
	v_add_f32_e32 v121, v123, v119
	v_mul_f32_e32 v120, 0xbfb8aa3b, v120
	v_mul_f32_e32 v121, 0xbfb8aa3b, v121
	v_exp_f32_e32 v120, v120
	v_exp_f32_e32 v121, v121
	v_cvt_pk_bf16_f32 v136, v137, v136
	v_pk_add_f32 v[120:121], v[120:121], 1.0 op_sel_hi:[1,0]
	s_nop 0
	s_nop 0
	v_rcp_f32_e32 v121, v121
	s_nop 0
	v_rcp_f32_e32 v120, v120
	s_nop 0
	v_cvt_pk_bf16_f32 v137, v120, v121
	global_load_dwordx4 v[120:123], v[134:135], off offset:96
	s_waitcnt vmcnt(0)
	v_add_f32_e32 v124, v124, v120
	v_add_f32_e32 v125, v125, v121
	v_mul_f32_e32 v124, 0xbfb8aa3b, v124
	v_mul_f32_e32 v125, 0xbfb8aa3b, v125
	v_exp_f32_e32 v124, v124
	v_exp_f32_e32 v125, v125
	s_nop 0
	v_pk_add_f32 v[124:125], v[124:125], 1.0 op_sel_hi:[1,0]
	s_nop 0
	s_nop 0
	v_rcp_f32_e32 v141, v125
	s_nop 0
	v_rcp_f32_e32 v142, v124
	v_add_f32_e32 v124, v126, v122
	v_add_f32_e32 v125, v127, v123
	v_mul_f32_e32 v124, 0xbfb8aa3b, v124
	v_mul_f32_e32 v125, 0xbfb8aa3b, v125
	v_exp_f32_e32 v124, v124
	v_exp_f32_e32 v125, v125
	s_nop 0
	v_pk_add_f32 v[124:125], v[124:125], 1.0 op_sel_hi:[1,0]
	s_nop 0
	s_nop 0
	v_rcp_f32_e32 v125, v125
	s_nop 0
	v_rcp_f32_e32 v126, v124
	v_cvt_pk_bf16_f32 v124, v142, v141
	v_cvt_pk_bf16_f32 v125, v126, v125
	ds_write2_b64 v132, v[136:137], v[124:125] offset0:4 offset1:6
	global_load_dwordx4 v[124:127], v[134:135], off offset:128
	s_waitcnt vmcnt(0)
	v_add_f32_e32 v96, v96, v124
	v_add_f32_e32 v97, v97, v125
	v_mul_f32_e32 v96, 0xbfb8aa3b, v96
	v_mul_f32_e32 v97, 0xbfb8aa3b, v97
	v_exp_f32_e32 v96, v96
	v_exp_f32_e32 v97, v97
	v_add_f32_e32 v64, v64, v124
	v_add_f32_e32 v65, v65, v125
	v_mul_f32_e32 v64, 0xbfb8aa3b, v64
	v_pk_add_f32 v[96:97], v[96:97], 1.0 op_sel_hi:[1,0]
	v_mul_f32_e32 v65, 0xbfb8aa3b, v65
	v_exp_f32_e32 v64, v64
	v_exp_f32_e32 v65, v65
	v_add_f32_e32 v32, v32, v124
	v_rcp_f32_e32 v136, v97
	v_pk_add_f32 v[64:65], v[64:65], 1.0 op_sel_hi:[1,0]
	v_add_f32_e32 v33, v33, v125
	v_mul_f32_e32 v32, 0xbfb8aa3b, v32
	v_rcp_f32_e32 v137, v96
	v_add_f32_e32 v96, v98, v126
	v_add_f32_e32 v97, v99, v127
	v_mul_f32_e32 v96, 0xbfb8aa3b, v96
	v_mul_f32_e32 v97, 0xbfb8aa3b, v97
	v_exp_f32_e32 v96, v96
	v_exp_f32_e32 v97, v97
	v_cvt_pk_bf16_f32 v136, v137, v136
	v_mul_f32_e32 v33, 0xbfb8aa3b, v33
	v_exp_f32_e32 v32, v32
	v_pk_add_f32 v[96:97], v[96:97], 1.0 op_sel_hi:[1,0]
	v_exp_f32_e32 v33, v33
	s_nop 0
	v_pk_add_f32 v[32:33], v[32:33], 1.0 op_sel_hi:[1,0]
	v_add_f32_e32 v0, v0, v124
	v_add_f32_e32 v1, v1, v125
	v_rcp_f32_e32 v97, v97
	v_mul_f32_e32 v0, 0xbfb8aa3b, v0
	v_mul_f32_e32 v1, 0xbfb8aa3b, v1
	v_exp_f32_e32 v0, v0
	v_rcp_f32_e32 v96, v96
	s_nop 0
	v_cvt_pk_bf16_f32 v137, v96, v97
	global_load_dwordx4 v[96:99], v[134:135], off offset:160
	v_exp_f32_e32 v1, v1
	s_waitcnt vmcnt(0)
	v_add_f32_e32 v100, v100, v96
	v_add_f32_e32 v101, v101, v97
	v_mul_f32_e32 v100, 0xbfb8aa3b, v100
	v_mul_f32_e32 v101, 0xbfb8aa3b, v101
	v_exp_f32_e32 v100, v100
	v_exp_f32_e32 v101, v101
	v_pk_add_f32 v[0:1], v[0:1], 1.0 op_sel_hi:[1,0]
	v_pk_add_f32 v[100:101], v[100:101], 1.0 op_sel_hi:[1,0]
	s_nop 0
	s_nop 0
	v_rcp_f32_e32 v141, v101
	s_nop 0
	v_rcp_f32_e32 v142, v100
	v_add_f32_e32 v100, v102, v98
	v_add_f32_e32 v101, v103, v99
	v_mul_f32_e32 v100, 0xbfb8aa3b, v100
	v_mul_f32_e32 v101, 0xbfb8aa3b, v101
	v_exp_f32_e32 v100, v100
	v_exp_f32_e32 v101, v101
	s_nop 0
	v_pk_add_f32 v[100:101], v[100:101], 1.0 op_sel_hi:[1,0]
	s_nop 0
	s_nop 0
	v_rcp_f32_e32 v101, v101
	s_nop 0
	v_rcp_f32_e32 v102, v100
	v_cvt_pk_bf16_f32 v100, v142, v141
	v_cvt_pk_bf16_f32 v101, v102, v101
	ds_write2_b64 v132, v[136:137], v[100:101] offset0:8 offset1:10
	global_load_dwordx4 v[100:103], v[134:135], off offset:192
	s_waitcnt vmcnt(0)
	v_add_f32_e32 v104, v104, v100
	v_add_f32_e32 v105, v105, v101
	v_mul_f32_e32 v104, 0xbfb8aa3b, v104
	v_mul_f32_e32 v105, 0xbfb8aa3b, v105
	v_exp_f32_e32 v104, v104
	v_exp_f32_e32 v105, v105
	s_nop 0
	v_pk_add_f32 v[104:105], v[104:105], 1.0 op_sel_hi:[1,0]
	s_nop 0
	s_nop 0
	v_rcp_f32_e32 v136, v105
	s_nop 0
	v_rcp_f32_e32 v137, v104
	v_add_f32_e32 v104, v106, v102
	v_add_f32_e32 v105, v107, v103
	v_mul_f32_e32 v104, 0xbfb8aa3b, v104
	v_mul_f32_e32 v105, 0xbfb8aa3b, v105
	v_exp_f32_e32 v104, v104
	v_exp_f32_e32 v105, v105
	v_cvt_pk_bf16_f32 v136, v137, v136
	v_pk_add_f32 v[104:105], v[104:105], 1.0 op_sel_hi:[1,0]
	s_nop 0
	s_nop 0
	v_rcp_f32_e32 v105, v105
	s_nop 0
	v_rcp_f32_e32 v104, v104
	s_nop 0
	v_cvt_pk_bf16_f32 v137, v104, v105
	global_load_dwordx4 v[104:107], v[134:135], off offset:224
	s_waitcnt vmcnt(0)
	v_add_f32_e32 v108, v108, v104
	v_add_f32_e32 v109, v109, v105
	v_mul_f32_e32 v108, 0xbfb8aa3b, v108
	v_mul_f32_e32 v109, 0xbfb8aa3b, v109
	v_exp_f32_e32 v108, v108
	v_exp_f32_e32 v109, v109
	s_nop 0
	v_pk_add_f32 v[108:109], v[108:109], 1.0 op_sel_hi:[1,0]
	s_nop 0
	s_nop 0
	v_rcp_f32_e32 v134, v109
	s_nop 0
	v_rcp_f32_e32 v135, v108
	v_add_f32_e32 v108, v110, v106
	v_add_f32_e32 v109, v111, v107
	v_mul_f32_e32 v108, 0xbfb8aa3b, v108
	v_mul_f32_e32 v109, 0xbfb8aa3b, v109
	v_exp_f32_e32 v108, v108
	v_exp_f32_e32 v109, v109
	s_nop 0
	v_pk_add_f32 v[108:109], v[108:109], 1.0 op_sel_hi:[1,0]
	s_nop 0
	s_nop 0
	v_rcp_f32_e32 v109, v109
	s_nop 0
	v_rcp_f32_e32 v110, v108
	v_cvt_pk_bf16_f32 v108, v135, v134
	v_cvt_pk_bf16_f32 v109, v110, v109
	ds_write2_b64 v132, v[136:137], v[108:109] offset0:12 offset1:14
	s_nop 0
	v_rcp_f32_e32 v108, v81
	s_nop 0
	v_rcp_f32_e32 v109, v80
	v_add_f32_e32 v80, v82, v130
	v_add_f32_e32 v81, v83, v131
	v_mul_f32_e32 v80, 0xbfb8aa3b, v80
	v_mul_f32_e32 v81, 0xbfb8aa3b, v81
	v_exp_f32_e32 v80, v80
	v_exp_f32_e32 v81, v81
	s_nop 0
	v_pk_add_f32 v[80:81], v[80:81], 1.0 op_sel_hi:[1,0]
	s_nop 0
	s_nop 0
	v_rcp_f32_e32 v81, v81
	s_nop 0
	v_rcp_f32_e32 v80, v80
	s_nop 0
	v_cvt_pk_bf16_f32 v83, v80, v81
	v_add_f32_e32 v80, v84, v112
	v_add_f32_e32 v81, v85, v113
	v_mul_f32_e32 v80, 0xbfb8aa3b, v80
	v_mul_f32_e32 v81, 0xbfb8aa3b, v81
	v_exp_f32_e32 v80, v80
	v_exp_f32_e32 v81, v81
	v_cvt_pk_bf16_f32 v82, v109, v108
	v_pk_add_f32 v[80:81], v[80:81], 1.0 op_sel_hi:[1,0]
	s_nop 0
	s_nop 0
	v_rcp_f32_e32 v84, v81
	s_nop 0
	v_rcp_f32_e32 v85, v80
	v_add_f32_e32 v80, v86, v114
	v_add_f32_e32 v81, v87, v115
	v_mul_f32_e32 v80, 0xbfb8aa3b, v80
	v_mul_f32_e32 v81, 0xbfb8aa3b, v81
	v_exp_f32_e32 v80, v80
	v_exp_f32_e32 v81, v81
	v_cvt_pk_bf16_f32 v84, v85, v84
	v_pk_add_f32 v[80:81], v[80:81], 1.0 op_sel_hi:[1,0]
	s_nop 0
	s_nop 0
	v_rcp_f32_e32 v81, v81
	s_nop 0
	v_rcp_f32_e32 v80, v80
	s_nop 0
	v_cvt_pk_bf16_f32 v85, v80, v81
	v_add_f32_e32 v81, v88, v116
	v_add_u32_e32 v80, 0x4000, v132
	v_mul_f32_e32 v81, 0xbfb8aa3b, v81
	ds_write2_b64 v80, v[82:83], v[84:85] offset0:64 offset1:66
	v_exp_f32_e32 v82, v81
	v_add_f32_e32 v81, v89, v117
	v_mul_f32_e32 v81, 0xbfb8aa3b, v81
	v_exp_f32_e32 v83, v81
	s_nop 0
	v_pk_add_f32 v[82:83], v[82:83], 1.0 op_sel_hi:[1,0]
	s_nop 0
	s_nop 0
	v_rcp_f32_e32 v81, v83
	s_nop 0
	v_rcp_f32_e32 v84, v82
	v_add_f32_e32 v82, v90, v118
	v_add_f32_e32 v83, v91, v119
	v_mul_f32_e32 v82, 0xbfb8aa3b, v82
	v_mul_f32_e32 v83, 0xbfb8aa3b, v83
	v_exp_f32_e32 v82, v82
	v_exp_f32_e32 v83, v83
	s_nop 0
	v_pk_add_f32 v[82:83], v[82:83], 1.0 op_sel_hi:[1,0]
	s_nop 0
	s_nop 0
	v_rcp_f32_e32 v83, v83
	s_nop 0
	v_rcp_f32_e32 v85, v82
	v_cvt_pk_bf16_f32 v82, v84, v81
	v_add_f32_e32 v81, v92, v120
	v_mul_f32_e32 v81, 0xbfb8aa3b, v81
	v_exp_f32_e32 v84, v81
	v_add_f32_e32 v81, v93, v121
	v_mul_f32_e32 v81, 0xbfb8aa3b, v81
	v_cvt_pk_bf16_f32 v83, v85, v83
	v_exp_f32_e32 v85, v81
	s_nop 0
	v_pk_add_f32 v[84:85], v[84:85], 1.0 op_sel_hi:[1,0]
	s_nop 0
	s_nop 0
	v_rcp_f32_e32 v81, v85
	s_nop 0
	v_rcp_f32_e32 v86, v84
	v_add_f32_e32 v84, v94, v122
	v_add_f32_e32 v85, v95, v123
	v_mul_f32_e32 v84, 0xbfb8aa3b, v84
	v_mul_f32_e32 v85, 0xbfb8aa3b, v85
	v_exp_f32_e32 v84, v84
	v_exp_f32_e32 v85, v85
	s_nop 0
	v_pk_add_f32 v[84:85], v[84:85], 1.0 op_sel_hi:[1,0]
	s_nop 0
	s_nop 0
	v_rcp_f32_e32 v85, v85
	s_nop 0
	v_rcp_f32_e32 v87, v84
	v_cvt_pk_bf16_f32 v84, v86, v81
	v_cvt_pk_bf16_f32 v85, v87, v85
	ds_write2_b64 v80, v[82:83], v[84:85] offset0:68 offset1:70
	s_nop 0
	v_rcp_f32_e32 v81, v65
	s_nop 0
	v_rcp_f32_e32 v82, v64
	v_add_f32_e32 v64, v66, v126
	v_add_f32_e32 v65, v67, v127
	v_mul_f32_e32 v64, 0xbfb8aa3b, v64
	v_mul_f32_e32 v65, 0xbfb8aa3b, v65
	v_exp_f32_e32 v64, v64
	v_exp_f32_e32 v65, v65
	s_nop 0
	v_pk_add_f32 v[64:65], v[64:65], 1.0 op_sel_hi:[1,0]
	s_nop 0
	s_nop 0
	v_rcp_f32_e32 v65, v65
	s_nop 0
	v_rcp_f32_e32 v66, v64
	s_nop 0
	v_cvt_pk_bf16_f32 v65, v66, v65
	v_add_f32_e32 v66, v68, v96
	v_add_f32_e32 v67, v69, v97
	v_mul_f32_e32 v66, 0xbfb8aa3b, v66
	v_mul_f32_e32 v67, 0xbfb8aa3b, v67
	v_exp_f32_e32 v66, v66
	v_exp_f32_e32 v67, v67
	v_cvt_pk_bf16_f32 v64, v82, v81
	v_pk_add_f32 v[66:67], v[66:67], 1.0 op_sel_hi:[1,0]
	s_nop 0
	s_nop 0
	v_rcp_f32_e32 v68, v67
	s_nop 0
	v_rcp_f32_e32 v69, v66
	v_add_f32_e32 v66, v70, v98
	v_add_f32_e32 v67, v71, v99
	v_mul_f32_e32 v66, 0xbfb8aa3b, v66
	v_mul_f32_e32 v67, 0xbfb8aa3b, v67
	v_exp_f32_e32 v66, v66
	v_exp_f32_e32 v67, v67
	s_nop 0
	v_pk_add_f32 v[66:67], v[66:67], 1.0 op_sel_hi:[1,0]
	s_nop 0
	s_nop 0
	v_rcp_f32_e32 v67, v67
	s_nop 0
	v_rcp_f32_e32 v70, v66
	v_cvt_pk_bf16_f32 v66, v69, v68
	v_cvt_pk_bf16_f32 v67, v70, v67
	ds_write2_b64 v80, v[64:65], v[66:67] offset0:72 offset1:74
	v_add_f32_e32 v64, v72, v100
	v_add_f32_e32 v65, v73, v101
	v_mul_f32_e32 v64, 0xbfb8aa3b, v64
	v_mul_f32_e32 v65, 0xbfb8aa3b, v65
	v_exp_f32_e32 v64, v64
	v_exp_f32_e32 v65, v65
	s_nop 0
	v_pk_add_f32 v[64:65], v[64:65], 1.0 op_sel_hi:[1,0]
	s_nop 0
	s_nop 0
	v_rcp_f32_e32 v66, v65
	s_nop 0
	v_rcp_f32_e32 v67, v64
	v_add_f32_e32 v64, v74, v102
	v_add_f32_e32 v65, v75, v103
	v_mul_f32_e32 v64, 0xbfb8aa3b, v64
	v_mul_f32_e32 v65, 0xbfb8aa3b, v65
	v_exp_f32_e32 v64, v64
	v_exp_f32_e32 v65, v65
	s_nop 0
	v_pk_add_f32 v[64:65], v[64:65], 1.0 op_sel_hi:[1,0]
	s_nop 0
	s_nop 0
	v_rcp_f32_e32 v65, v65
	s_nop 0
	v_rcp_f32_e32 v68, v64
	v_cvt_pk_bf16_f32 v64, v67, v66
	v_add_f32_e32 v66, v76, v104
	v_add_f32_e32 v67, v77, v105
	v_mul_f32_e32 v66, 0xbfb8aa3b, v66
	v_mul_f32_e32 v67, 0xbfb8aa3b, v67
	v_exp_f32_e32 v66, v66
	v_exp_f32_e32 v67, v67
	v_cvt_pk_bf16_f32 v65, v68, v65
	v_pk_add_f32 v[66:67], v[66:67], 1.0 op_sel_hi:[1,0]
	s_nop 0
	s_nop 0
	v_rcp_f32_e32 v68, v67
	s_nop 0
	v_rcp_f32_e32 v69, v66
	v_add_f32_e32 v66, v78, v106
	v_add_f32_e32 v67, v79, v107
	v_mul_f32_e32 v66, 0xbfb8aa3b, v66
	v_mul_f32_e32 v67, 0xbfb8aa3b, v67
	v_exp_f32_e32 v66, v66
	v_exp_f32_e32 v67, v67
	s_nop 0
	v_pk_add_f32 v[66:67], v[66:67], 1.0 op_sel_hi:[1,0]
	s_nop 0
	s_nop 0
	v_rcp_f32_e32 v67, v67
	s_nop 0
	v_rcp_f32_e32 v70, v66
	v_cvt_pk_bf16_f32 v66, v69, v68
	v_cvt_pk_bf16_f32 v67, v70, v67
	ds_write2_b64 v80, v[64:65], v[66:67] offset0:76 offset1:78
	s_nop 0
	v_rcp_f32_e32 v64, v49
	s_nop 0
	v_rcp_f32_e32 v65, v48
	v_add_f32_e32 v48, v50, v130
	v_add_f32_e32 v49, v51, v131
	v_mul_f32_e32 v48, 0xbfb8aa3b, v48
	v_mul_f32_e32 v49, 0xbfb8aa3b, v49
	v_exp_f32_e32 v48, v48
	v_exp_f32_e32 v49, v49
	s_nop 0
	v_pk_add_f32 v[48:49], v[48:49], 1.0 op_sel_hi:[1,0]
	s_nop 0
	s_nop 0
	v_rcp_f32_e32 v49, v49
	s_nop 0
	v_rcp_f32_e32 v48, v48
	s_nop 0
	v_cvt_pk_bf16_f32 v51, v48, v49
	v_add_f32_e32 v48, v52, v112
	v_add_f32_e32 v49, v53, v113
	v_mul_f32_e32 v48, 0xbfb8aa3b, v48
	v_mul_f32_e32 v49, 0xbfb8aa3b, v49
	v_exp_f32_e32 v48, v48
	v_exp_f32_e32 v49, v49
	v_cvt_pk_bf16_f32 v50, v65, v64
	v_pk_add_f32 v[48:49], v[48:49], 1.0 op_sel_hi:[1,0]
	s_nop 0
	s_nop 0
	v_rcp_f32_e32 v52, v49
	s_nop 0
	v_rcp_f32_e32 v53, v48
	v_add_f32_e32 v48, v54, v114
	v_add_f32_e32 v49, v55, v115
	v_mul_f32_e32 v48, 0xbfb8aa3b, v48
	v_mul_f32_e32 v49, 0xbfb8aa3b, v49
	v_exp_f32_e32 v48, v48
	v_exp_f32_e32 v49, v49
	v_cvt_pk_bf16_f32 v52, v53, v52
	v_pk_add_f32 v[48:49], v[48:49], 1.0 op_sel_hi:[1,0]
	s_nop 0
	s_nop 0
	v_rcp_f32_e32 v49, v49
	s_nop 0
	v_rcp_f32_e32 v48, v48
	s_nop 0
	v_cvt_pk_bf16_f32 v53, v48, v49
	v_add_f32_e32 v49, v56, v116
	v_add_u32_e32 v48, 0x8000, v132
	v_mul_f32_e32 v49, 0xbfb8aa3b, v49
	ds_write2_b64 v48, v[50:51], v[52:53] offset0:128 offset1:130
	v_exp_f32_e32 v50, v49
	v_add_f32_e32 v49, v57, v117
	v_mul_f32_e32 v49, 0xbfb8aa3b, v49
	v_exp_f32_e32 v51, v49
	s_nop 0
	v_pk_add_f32 v[50:51], v[50:51], 1.0 op_sel_hi:[1,0]
	s_nop 0
	s_nop 0
	v_rcp_f32_e32 v49, v51
	s_nop 0
	v_rcp_f32_e32 v52, v50
	v_add_f32_e32 v50, v58, v118
	v_add_f32_e32 v51, v59, v119
	v_mul_f32_e32 v50, 0xbfb8aa3b, v50
	v_mul_f32_e32 v51, 0xbfb8aa3b, v51
	v_exp_f32_e32 v50, v50
	v_exp_f32_e32 v51, v51
	s_nop 0
	v_pk_add_f32 v[50:51], v[50:51], 1.0 op_sel_hi:[1,0]
	s_nop 0
	s_nop 0
	v_rcp_f32_e32 v51, v51
	s_nop 0
	v_rcp_f32_e32 v53, v50
	v_cvt_pk_bf16_f32 v50, v52, v49
	v_add_f32_e32 v49, v60, v120
	v_mul_f32_e32 v49, 0xbfb8aa3b, v49
	v_exp_f32_e32 v52, v49
	v_add_f32_e32 v49, v61, v121
	v_mul_f32_e32 v49, 0xbfb8aa3b, v49
	v_cvt_pk_bf16_f32 v51, v53, v51
	v_exp_f32_e32 v53, v49
	s_nop 0
	v_pk_add_f32 v[52:53], v[52:53], 1.0 op_sel_hi:[1,0]
	s_nop 0
	s_nop 0
	v_rcp_f32_e32 v49, v53
	s_nop 0
	v_rcp_f32_e32 v54, v52
	v_add_f32_e32 v52, v62, v122
	v_add_f32_e32 v53, v63, v123
	v_mul_f32_e32 v52, 0xbfb8aa3b, v52
	v_mul_f32_e32 v53, 0xbfb8aa3b, v53
	v_exp_f32_e32 v52, v52
	v_exp_f32_e32 v53, v53
	s_nop 0
	v_pk_add_f32 v[52:53], v[52:53], 1.0 op_sel_hi:[1,0]
	s_nop 0
	s_nop 0
	v_rcp_f32_e32 v53, v53
	s_nop 0
	v_rcp_f32_e32 v55, v52
	v_cvt_pk_bf16_f32 v52, v54, v49
	v_cvt_pk_bf16_f32 v53, v55, v53
	ds_write2_b64 v48, v[50:51], v[52:53] offset0:132 offset1:134
	s_nop 0
	v_rcp_f32_e32 v49, v33
	s_nop 0
	v_rcp_f32_e32 v50, v32
	v_add_f32_e32 v32, v34, v126
	v_add_f32_e32 v33, v35, v127
	v_mul_f32_e32 v32, 0xbfb8aa3b, v32
	v_mul_f32_e32 v33, 0xbfb8aa3b, v33
	v_exp_f32_e32 v32, v32
	v_exp_f32_e32 v33, v33
	s_nop 0
	v_pk_add_f32 v[32:33], v[32:33], 1.0 op_sel_hi:[1,0]
	s_nop 0
	s_nop 0
	v_rcp_f32_e32 v33, v33
	s_nop 0
	v_rcp_f32_e32 v34, v32
	s_nop 0
	v_cvt_pk_bf16_f32 v33, v34, v33
	v_add_f32_e32 v34, v36, v96
	v_add_f32_e32 v35, v37, v97
	v_mul_f32_e32 v34, 0xbfb8aa3b, v34
	v_mul_f32_e32 v35, 0xbfb8aa3b, v35
	v_exp_f32_e32 v34, v34
	v_exp_f32_e32 v35, v35
	v_cvt_pk_bf16_f32 v32, v50, v49
	v_pk_add_f32 v[34:35], v[34:35], 1.0 op_sel_hi:[1,0]
	s_nop 0
	s_nop 0
	v_rcp_f32_e32 v36, v35
	s_nop 0
	v_rcp_f32_e32 v37, v34
	v_add_f32_e32 v34, v38, v98
	v_add_f32_e32 v35, v39, v99
	v_mul_f32_e32 v34, 0xbfb8aa3b, v34
	v_mul_f32_e32 v35, 0xbfb8aa3b, v35
	v_exp_f32_e32 v34, v34
	v_exp_f32_e32 v35, v35
	s_nop 0
	v_pk_add_f32 v[34:35], v[34:35], 1.0 op_sel_hi:[1,0]
	s_nop 0
	s_nop 0
	v_rcp_f32_e32 v35, v35
	s_nop 0
	v_rcp_f32_e32 v38, v34
	v_cvt_pk_bf16_f32 v34, v37, v36
	v_cvt_pk_bf16_f32 v35, v38, v35
	ds_write2_b64 v48, v[32:33], v[34:35] offset0:136 offset1:138
	v_add_f32_e32 v32, v40, v100
	v_add_f32_e32 v33, v41, v101
	v_mul_f32_e32 v32, 0xbfb8aa3b, v32
	v_mul_f32_e32 v33, 0xbfb8aa3b, v33
	v_exp_f32_e32 v32, v32
	v_exp_f32_e32 v33, v33
	s_nop 0
	v_pk_add_f32 v[32:33], v[32:33], 1.0 op_sel_hi:[1,0]
	s_nop 0
	s_nop 0
	v_rcp_f32_e32 v34, v33
	s_nop 0
	v_rcp_f32_e32 v35, v32
	v_add_f32_e32 v32, v42, v102
	v_add_f32_e32 v33, v43, v103
	v_mul_f32_e32 v32, 0xbfb8aa3b, v32
	v_mul_f32_e32 v33, 0xbfb8aa3b, v33
	v_exp_f32_e32 v32, v32
	v_exp_f32_e32 v33, v33
	s_nop 0
	v_pk_add_f32 v[32:33], v[32:33], 1.0 op_sel_hi:[1,0]
	s_nop 0
	s_nop 0
	v_rcp_f32_e32 v33, v33
	s_nop 0
	v_rcp_f32_e32 v36, v32
	v_cvt_pk_bf16_f32 v32, v35, v34
	v_add_f32_e32 v34, v44, v104
	v_add_f32_e32 v35, v45, v105
	v_mul_f32_e32 v34, 0xbfb8aa3b, v34
	v_mul_f32_e32 v35, 0xbfb8aa3b, v35
	v_exp_f32_e32 v34, v34
	v_exp_f32_e32 v35, v35
	v_cvt_pk_bf16_f32 v33, v36, v33
	v_pk_add_f32 v[34:35], v[34:35], 1.0 op_sel_hi:[1,0]
	s_nop 0
	s_nop 0
	v_rcp_f32_e32 v36, v35
	s_nop 0
	v_rcp_f32_e32 v37, v34
	v_add_f32_e32 v34, v46, v106
	v_add_f32_e32 v35, v47, v107
	v_mul_f32_e32 v34, 0xbfb8aa3b, v34
	v_mul_f32_e32 v35, 0xbfb8aa3b, v35
	v_exp_f32_e32 v34, v34
	v_exp_f32_e32 v35, v35
	s_nop 0
	v_pk_add_f32 v[34:35], v[34:35], 1.0 op_sel_hi:[1,0]
	s_nop 0
	s_nop 0
	v_rcp_f32_e32 v35, v35
	s_nop 0
	v_rcp_f32_e32 v38, v34
	v_cvt_pk_bf16_f32 v34, v37, v36
	v_cvt_pk_bf16_f32 v35, v38, v35
	ds_write2_b64 v48, v[32:33], v[34:35] offset0:140 offset1:142
	s_nop 0
	v_rcp_f32_e32 v32, v17
	s_nop 0
	v_rcp_f32_e32 v33, v16
	v_add_f32_e32 v16, v18, v130
	v_add_f32_e32 v17, v19, v131
	v_mul_f32_e32 v16, 0xbfb8aa3b, v16
	v_mul_f32_e32 v17, 0xbfb8aa3b, v17
	v_exp_f32_e32 v16, v16
	v_exp_f32_e32 v17, v17
	s_nop 0
	v_pk_add_f32 v[16:17], v[16:17], 1.0 op_sel_hi:[1,0]
	s_nop 0
	s_nop 0
	v_rcp_f32_e32 v17, v17
	s_nop 0
	v_rcp_f32_e32 v16, v16
	s_nop 0
	v_cvt_pk_bf16_f32 v19, v16, v17
	v_add_f32_e32 v16, v20, v112
	v_add_f32_e32 v17, v21, v113
	v_mul_f32_e32 v16, 0xbfb8aa3b, v16
	v_mul_f32_e32 v17, 0xbfb8aa3b, v17
	v_exp_f32_e32 v16, v16
	v_exp_f32_e32 v17, v17
	v_cvt_pk_bf16_f32 v18, v33, v32
	v_pk_add_f32 v[16:17], v[16:17], 1.0 op_sel_hi:[1,0]
	s_nop 0
	s_nop 0
	v_rcp_f32_e32 v20, v17
	s_nop 0
	v_rcp_f32_e32 v21, v16
	v_add_f32_e32 v16, v22, v114
	v_add_f32_e32 v17, v23, v115
	v_mul_f32_e32 v16, 0xbfb8aa3b, v16
	v_mul_f32_e32 v17, 0xbfb8aa3b, v17
	v_exp_f32_e32 v16, v16
	v_exp_f32_e32 v17, v17
	v_cvt_pk_bf16_f32 v20, v21, v20
	v_pk_add_f32 v[16:17], v[16:17], 1.0 op_sel_hi:[1,0]
	s_nop 0
	s_nop 0
	v_rcp_f32_e32 v17, v17
	s_nop 0
	v_rcp_f32_e32 v16, v16
	s_nop 0
	v_cvt_pk_bf16_f32 v21, v16, v17
	v_add_f32_e32 v17, v24, v116
	v_add_u32_e32 v16, 0xc000, v132
	v_mul_f32_e32 v17, 0xbfb8aa3b, v17
	ds_write2_b64 v16, v[18:19], v[20:21] offset0:192 offset1:194
	v_exp_f32_e32 v18, v17
	v_add_f32_e32 v17, v25, v117
	v_mul_f32_e32 v17, 0xbfb8aa3b, v17
	v_exp_f32_e32 v19, v17
	s_nop 0
	v_pk_add_f32 v[18:19], v[18:19], 1.0 op_sel_hi:[1,0]
	s_nop 0
	s_nop 0
	v_rcp_f32_e32 v17, v19
	s_nop 0
	v_rcp_f32_e32 v20, v18
	v_add_f32_e32 v18, v26, v118
	v_add_f32_e32 v19, v27, v119
	v_mul_f32_e32 v18, 0xbfb8aa3b, v18
	v_mul_f32_e32 v19, 0xbfb8aa3b, v19
	v_exp_f32_e32 v18, v18
	v_exp_f32_e32 v19, v19
	s_nop 0
	v_pk_add_f32 v[18:19], v[18:19], 1.0 op_sel_hi:[1,0]
	s_nop 0
	s_nop 0
	v_rcp_f32_e32 v19, v19
	s_nop 0
	v_rcp_f32_e32 v21, v18
	v_cvt_pk_bf16_f32 v18, v20, v17
	v_add_f32_e32 v17, v28, v120
	v_mul_f32_e32 v17, 0xbfb8aa3b, v17
	v_exp_f32_e32 v20, v17
	v_add_f32_e32 v17, v29, v121
	v_mul_f32_e32 v17, 0xbfb8aa3b, v17
	v_cvt_pk_bf16_f32 v19, v21, v19
	v_exp_f32_e32 v21, v17
	s_nop 0
	v_pk_add_f32 v[20:21], v[20:21], 1.0 op_sel_hi:[1,0]
	s_nop 0
	s_nop 0
	v_rcp_f32_e32 v17, v21
	s_nop 0
	v_rcp_f32_e32 v22, v20
	v_add_f32_e32 v20, v30, v122
	v_add_f32_e32 v21, v31, v123
	v_mul_f32_e32 v20, 0xbfb8aa3b, v20
	v_mul_f32_e32 v21, 0xbfb8aa3b, v21
	v_exp_f32_e32 v20, v20
	v_exp_f32_e32 v21, v21
	s_nop 0
	v_pk_add_f32 v[20:21], v[20:21], 1.0 op_sel_hi:[1,0]
	s_nop 0
	s_nop 0
	v_rcp_f32_e32 v21, v21
	s_nop 0
	v_rcp_f32_e32 v23, v20
	v_cvt_pk_bf16_f32 v20, v22, v17
	v_cvt_pk_bf16_f32 v21, v23, v21
	ds_write2_b64 v16, v[18:19], v[20:21] offset0:196 offset1:198
	s_nop 0
	v_rcp_f32_e32 v17, v1
	s_nop 0
	v_rcp_f32_e32 v18, v0
	v_add_f32_e32 v0, v2, v126
	v_add_f32_e32 v1, v3, v127
	v_mul_f32_e32 v0, 0xbfb8aa3b, v0
	v_mul_f32_e32 v1, 0xbfb8aa3b, v1
	v_exp_f32_e32 v0, v0
	v_exp_f32_e32 v1, v1
	s_nop 0
	v_pk_add_f32 v[0:1], v[0:1], 1.0 op_sel_hi:[1,0]
	s_nop 0
	s_nop 0
	v_rcp_f32_e32 v1, v1
	s_nop 0
	v_rcp_f32_e32 v2, v0
	s_nop 0
	v_cvt_pk_bf16_f32 v1, v2, v1
	v_add_f32_e32 v2, v4, v96
	v_add_f32_e32 v3, v5, v97
	v_mul_f32_e32 v2, 0xbfb8aa3b, v2
	v_mul_f32_e32 v3, 0xbfb8aa3b, v3
	v_exp_f32_e32 v2, v2
	v_exp_f32_e32 v3, v3
	v_cvt_pk_bf16_f32 v0, v18, v17
	v_pk_add_f32 v[2:3], v[2:3], 1.0 op_sel_hi:[1,0]
	s_nop 0
	s_nop 0
	v_rcp_f32_e32 v4, v3
	s_nop 0
	v_rcp_f32_e32 v5, v2
	v_add_f32_e32 v2, v6, v98
	v_add_f32_e32 v3, v7, v99
	v_mul_f32_e32 v2, 0xbfb8aa3b, v2
	v_mul_f32_e32 v3, 0xbfb8aa3b, v3
	v_exp_f32_e32 v2, v2
	v_exp_f32_e32 v3, v3
	s_nop 0
	v_pk_add_f32 v[2:3], v[2:3], 1.0 op_sel_hi:[1,0]
	s_nop 0
	s_nop 0
	v_rcp_f32_e32 v3, v3
	s_nop 0
	v_rcp_f32_e32 v6, v2
	v_cvt_pk_bf16_f32 v2, v5, v4
	v_cvt_pk_bf16_f32 v3, v6, v3
	ds_write2_b64 v16, v[0:1], v[2:3] offset0:200 offset1:202
	v_add_f32_e32 v0, v8, v100
	v_add_f32_e32 v1, v9, v101
	v_mul_f32_e32 v0, 0xbfb8aa3b, v0
	v_mul_f32_e32 v1, 0xbfb8aa3b, v1
	v_exp_f32_e32 v0, v0
	v_exp_f32_e32 v1, v1
	s_nop 0
	v_pk_add_f32 v[0:1], v[0:1], 1.0 op_sel_hi:[1,0]
	s_nop 0
	s_nop 0
	v_rcp_f32_e32 v2, v1
	s_nop 0
	v_rcp_f32_e32 v3, v0
	v_add_f32_e32 v0, v10, v102
	v_add_f32_e32 v1, v11, v103
	v_mul_f32_e32 v0, 0xbfb8aa3b, v0
	v_mul_f32_e32 v1, 0xbfb8aa3b, v1
	v_exp_f32_e32 v0, v0
	v_exp_f32_e32 v1, v1
	s_nop 0
	v_pk_add_f32 v[0:1], v[0:1], 1.0 op_sel_hi:[1,0]
	s_nop 0
	s_nop 0
	v_rcp_f32_e32 v1, v1
	s_nop 0
	v_rcp_f32_e32 v4, v0
	v_cvt_pk_bf16_f32 v0, v3, v2
	v_add_f32_e32 v2, v12, v104
	v_add_f32_e32 v3, v13, v105
	v_mul_f32_e32 v2, 0xbfb8aa3b, v2
	v_mul_f32_e32 v3, 0xbfb8aa3b, v3
	v_exp_f32_e32 v2, v2
	v_exp_f32_e32 v3, v3
	v_cvt_pk_bf16_f32 v1, v4, v1
	v_pk_add_f32 v[2:3], v[2:3], 1.0 op_sel_hi:[1,0]
	s_nop 0
	s_nop 0
	v_rcp_f32_e32 v4, v3
	s_nop 0
	v_rcp_f32_e32 v5, v2
	v_add_f32_e32 v2, v14, v106
	v_add_f32_e32 v3, v15, v107
	v_mul_f32_e32 v2, 0xbfb8aa3b, v2
	v_mul_f32_e32 v3, 0xbfb8aa3b, v3
	v_exp_f32_e32 v2, v2
	v_exp_f32_e32 v3, v3
	s_nop 0
	v_pk_add_f32 v[2:3], v[2:3], 1.0 op_sel_hi:[1,0]
	s_nop 0
	s_nop 0
	v_rcp_f32_e32 v3, v3
	s_nop 0
	v_rcp_f32_e32 v6, v2
	v_cvt_pk_bf16_f32 v2, v5, v4
	v_cvt_pk_bf16_f32 v3, v6, v3
	ds_write2_b64 v16, v[0:1], v[2:3] offset0:204 offset1:206
	v_mov_b32_e32 v1, v176
	s_waitcnt lgkmcnt(0)
	s_barrier
	s_nop 0
	v_lshlrev_b32_e32 v0, 3, v1
	v_and_b32_e32 v0, 0xf8, v0
	v_or_b32_e32 v2, s68, v0
	v_lshlrev_b32_e32 v132, 1, v2
	v_lshlrev_b32_e32 v0, 1, v0
	v_lshl_add_u64 v[2:3], s[64:65], 0, v[132:133]

.LBB0_1041:
	v_mov_b32_e32 v128, v176
	s_waitcnt vmcnt(0) lgkmcnt(0)
	s_barrier
	s_lshl_b32 s62, s67, 8
	v_and_b32_e32 v129, 0xc0, v128
	v_and_b32_e32 v130, 31, v128
	v_lshrrev_b32_e32 v131, 1, v128
	v_lshrrev_b32_e32 v128, 3, v128
	v_and_or_b32 v142, v128, 4, v129
	v_or_b32_e32 v132, s62, v142
	v_and_or_b32 v130, v131, s93, v130
	v_lshl_add_u64 v[134:135], v[132:133], 2, s[86:87]
	v_mul_lo_u32 v143, v130, s0
	global_load_dwordx4 v[128:131], v[134:135], off
	s_mov_b32 s3, 0
	s_waitcnt vmcnt(0)
	v_add_f32_e32 v112, v112, v128
	v_add_f32_e32 v113, v113, v129
	v_mul_f32_e32 v112, 0xbfb8aa3b, v112
	v_mul_f32_e32 v113, 0xbfb8aa3b, v113
	v_exp_f32_e32 v112, v112
	v_exp_f32_e32 v113, v113
	v_add_f32_e32 v80, v80, v128
	v_add_f32_e32 v81, v81, v129
	v_mul_f32_e32 v80, 0xbfb8aa3b, v80
	v_pk_add_f32 v[112:113], v[112:113], 1.0 op_sel_hi:[1,0]
	v_mul_f32_e32 v81, 0xbfb8aa3b, v81
	v_exp_f32_e32 v80, v80
	v_exp_f32_e32 v81, v81
	v_add_f32_e32 v48, v48, v128
	v_rcp_f32_e32 v132, v113
	v_pk_add_f32 v[80:81], v[80:81], 1.0 op_sel_hi:[1,0]
	v_add_f32_e32 v49, v49, v129
	v_mul_f32_e32 v48, 0xbfb8aa3b, v48
	v_rcp_f32_e32 v136, v112
	v_add_f32_e32 v112, v114, v130
	v_add_f32_e32 v113, v115, v131
	v_mul_f32_e32 v112, 0xbfb8aa3b, v112
	v_mul_f32_e32 v113, 0xbfb8aa3b, v113
	v_exp_f32_e32 v112, v112
	v_exp_f32_e32 v113, v113
	v_cvt_pk_bf16_f32 v136, v136, v132
	v_lshl_add_u32 v132, v142, 1, v143
	v_mul_f32_e32 v49, 0xbfb8aa3b, v49
	v_pk_add_f32 v[112:113], v[112:113], 1.0 op_sel_hi:[1,0]
	v_exp_f32_e32 v48, v48
	v_exp_f32_e32 v49, v49
	v_add_f32_e32 v16, v16, v128
	v_add_f32_e32 v17, v17, v129
	v_rcp_f32_e32 v113, v113
	v_pk_add_f32 v[48:49], v[48:49], 1.0 op_sel_hi:[1,0]
	v_mul_f32_e32 v16, 0xbfb8aa3b, v16
	v_mul_f32_e32 v17, 0xbfb8aa3b, v17
	v_rcp_f32_e32 v112, v112
	s_nop 0
	v_cvt_pk_bf16_f32 v137, v112, v113
	global_load_dwordx4 v[112:115], v[134:135], off offset:32
	v_exp_f32_e32 v16, v16
	v_exp_f32_e32 v17, v17
	s_waitcnt vmcnt(0)
	v_add_f32_e32 v116, v116, v112
	v_add_f32_e32 v117, v117, v113
	v_mul_f32_e32 v116, 0xbfb8aa3b, v116
	v_mul_f32_e32 v117, 0xbfb8aa3b, v117
	v_exp_f32_e32 v116, v116
	v_exp_f32_e32 v117, v117
	v_pk_add_f32 v[16:17], v[16:17], 1.0 op_sel_hi:[1,0]
	v_pk_add_f32 v[116:117], v[116:117], 1.0 op_sel_hi:[1,0]
	s_nop 0
	s_nop 0
	v_rcp_f32_e32 v142, v117
	s_nop 0
	v_rcp_f32_e32 v143, v116
	v_add_f32_e32 v116, v118, v114
	v_add_f32_e32 v117, v119, v115
	v_mul_f32_e32 v116, 0xbfb8aa3b, v116
	v_mul_f32_e32 v117, 0xbfb8aa3b, v117
	v_exp_f32_e32 v116, v116
	v_exp_f32_e32 v117, v117
	s_nop 0
	v_pk_add_f32 v[116:117], v[116:117], 1.0 op_sel_hi:[1,0]
	s_nop 0
	s_nop 0
	v_rcp_f32_e32 v117, v117
	s_nop 0
	v_rcp_f32_e32 v118, v116
	v_cvt_pk_bf16_f32 v116, v143, v142
	v_cvt_pk_bf16_f32 v117, v118, v117
	ds_write2_b64 v132, v[136:137], v[116:117] offset1:2
	global_load_dwordx4 v[116:119], v[134:135], off offset:64
	s_waitcnt vmcnt(0)
	v_add_f32_e32 v120, v120, v116
	v_add_f32_e32 v121, v121, v117
	v_mul_f32_e32 v120, 0xbfb8aa3b, v120
	v_mul_f32_e32 v121, 0xbfb8aa3b, v121
	v_exp_f32_e32 v120, v120
	v_exp_f32_e32 v121, v121
	s_nop 0
	v_pk_add_f32 v[120:121], v[120:121], 1.0 op_sel_hi:[1,0]
	s_nop 0
	s_nop 0
	v_rcp_f32_e32 v136, v121
	s_nop 0
	v_rcp_f32_e32 v137, v120
	v_add_f32_e32 v120, v122, v118
	v_add_f32_e32 v121, v123, v119
	v_mul_f32_e32 v120, 0xbfb8aa3b, v120
	v_mul_f32_e32 v121, 0xbfb8aa3b, v121
	v_exp_f32_e32 v120, v120
	v_exp_f32_e32 v121, v121
	v_cvt_pk_bf16_f32 v136, v137, v136
	v_pk_add_f32 v[120:121], v[120:121], 1.0 op_sel_hi:[1,0]
	s_nop 0
	s_nop 0
	v_rcp_f32_e32 v121, v121
	s_nop 0
	v_rcp_f32_e32 v120, v120
	s_nop 0
	v_cvt_pk_bf16_f32 v137, v120, v121
	global_load_dwordx4 v[120:123], v[134:135], off offset:96
	s_waitcnt vmcnt(0)
	v_add_f32_e32 v124, v124, v120
	v_add_f32_e32 v125, v125, v121
	v_mul_f32_e32 v124, 0xbfb8aa3b, v124
	v_mul_f32_e32 v125, 0xbfb8aa3b, v125
	v_exp_f32_e32 v124, v124
	v_exp_f32_e32 v125, v125
	s_nop 0
	v_pk_add_f32 v[124:125], v[124:125], 1.0 op_sel_hi:[1,0]
	s_nop 0
	s_nop 0
	v_rcp_f32_e32 v142, v125
	s_nop 0
	v_rcp_f32_e32 v143, v124
	v_add_f32_e32 v124, v126, v122
	v_add_f32_e32 v125, v127, v123
	v_mul_f32_e32 v124, 0xbfb8aa3b, v124
	v_mul_f32_e32 v125, 0xbfb8aa3b, v125
	v_exp_f32_e32 v124, v124
	v_exp_f32_e32 v125, v125
	s_nop 0
	v_pk_add_f32 v[124:125], v[124:125], 1.0 op_sel_hi:[1,0]
	s_nop 0
	s_nop 0
	v_rcp_f32_e32 v125, v125
	s_nop 0
	v_rcp_f32_e32 v126, v124
	v_cvt_pk_bf16_f32 v124, v143, v142
	v_cvt_pk_bf16_f32 v125, v126, v125
	ds_write2_b64 v132, v[136:137], v[124:125] offset0:4 offset1:6
	global_load_dwordx4 v[124:127], v[134:135], off offset:128
	s_waitcnt vmcnt(0)
	v_add_f32_e32 v96, v96, v124
	v_add_f32_e32 v97, v97, v125
	v_mul_f32_e32 v96, 0xbfb8aa3b, v96
	v_mul_f32_e32 v97, 0xbfb8aa3b, v97
	v_exp_f32_e32 v96, v96
	v_exp_f32_e32 v97, v97
	v_add_f32_e32 v64, v64, v124
	v_add_f32_e32 v65, v65, v125
	v_mul_f32_e32 v64, 0xbfb8aa3b, v64
	v_pk_add_f32 v[96:97], v[96:97], 1.0 op_sel_hi:[1,0]
	v_mul_f32_e32 v65, 0xbfb8aa3b, v65
	v_exp_f32_e32 v64, v64
	v_exp_f32_e32 v65, v65
	v_add_f32_e32 v32, v32, v124
	v_rcp_f32_e32 v136, v97
	v_pk_add_f32 v[64:65], v[64:65], 1.0 op_sel_hi:[1,0]
	v_add_f32_e32 v33, v33, v125
	v_mul_f32_e32 v32, 0xbfb8aa3b, v32
	v_rcp_f32_e32 v137, v96
	v_add_f32_e32 v96, v98, v126
	v_add_f32_e32 v97, v99, v127
	v_mul_f32_e32 v96, 0xbfb8aa3b, v96
	v_mul_f32_e32 v97, 0xbfb8aa3b, v97
	v_exp_f32_e32 v96, v96
	v_exp_f32_e32 v97, v97
	v_cvt_pk_bf16_f32 v136, v137, v136
	v_mul_f32_e32 v33, 0xbfb8aa3b, v33
	v_exp_f32_e32 v32, v32
	v_pk_add_f32 v[96:97], v[96:97], 1.0 op_sel_hi:[1,0]
	v_exp_f32_e32 v33, v33
	s_nop 0
	v_pk_add_f32 v[32:33], v[32:33], 1.0 op_sel_hi:[1,0]
	v_add_f32_e32 v0, v0, v124
	v_add_f32_e32 v1, v1, v125
	v_rcp_f32_e32 v97, v97
	v_mul_f32_e32 v0, 0xbfb8aa3b, v0
	v_mul_f32_e32 v1, 0xbfb8aa3b, v1
	v_exp_f32_e32 v0, v0
	v_rcp_f32_e32 v96, v96
	s_nop 0
	v_cvt_pk_bf16_f32 v137, v96, v97
	global_load_dwordx4 v[96:99], v[134:135], off offset:160
	v_exp_f32_e32 v1, v1
	s_waitcnt vmcnt(0)
	v_add_f32_e32 v100, v100, v96
	v_add_f32_e32 v101, v101, v97
	v_mul_f32_e32 v100, 0xbfb8aa3b, v100
	v_mul_f32_e32 v101, 0xbfb8aa3b, v101
	v_exp_f32_e32 v100, v100
	v_exp_f32_e32 v101, v101
	v_pk_add_f32 v[0:1], v[0:1], 1.0 op_sel_hi:[1,0]
	v_pk_add_f32 v[100:101], v[100:101], 1.0 op_sel_hi:[1,0]
	s_nop 0
	s_nop 0
	v_rcp_f32_e32 v142, v101
	s_nop 0
	v_rcp_f32_e32 v143, v100
	v_add_f32_e32 v100, v102, v98
	v_add_f32_e32 v101, v103, v99
	v_mul_f32_e32 v100, 0xbfb8aa3b, v100
	v_mul_f32_e32 v101, 0xbfb8aa3b, v101
	v_exp_f32_e32 v100, v100
	v_exp_f32_e32 v101, v101
	s_nop 0
	v_pk_add_f32 v[100:101], v[100:101], 1.0 op_sel_hi:[1,0]
	s_nop 0
	s_nop 0
	v_rcp_f32_e32 v101, v101
	s_nop 0
	v_rcp_f32_e32 v102, v100
	v_cvt_pk_bf16_f32 v100, v143, v142
	v_cvt_pk_bf16_f32 v101, v102, v101
	ds_write2_b64 v132, v[136:137], v[100:101] offset0:8 offset1:10
	global_load_dwordx4 v[100:103], v[134:135], off offset:192
	s_waitcnt vmcnt(0)
	v_add_f32_e32 v104, v104, v100
	v_add_f32_e32 v105, v105, v101
	v_mul_f32_e32 v104, 0xbfb8aa3b, v104
	v_mul_f32_e32 v105, 0xbfb8aa3b, v105
	v_exp_f32_e32 v104, v104
	v_exp_f32_e32 v105, v105
	s_nop 0
	v_pk_add_f32 v[104:105], v[104:105], 1.0 op_sel_hi:[1,0]
	s_nop 0
	s_nop 0
	v_rcp_f32_e32 v136, v105
	s_nop 0
	v_rcp_f32_e32 v137, v104
	v_add_f32_e32 v104, v106, v102
	v_add_f32_e32 v105, v107, v103
	v_mul_f32_e32 v104, 0xbfb8aa3b, v104
	v_mul_f32_e32 v105, 0xbfb8aa3b, v105
	v_exp_f32_e32 v104, v104
	v_exp_f32_e32 v105, v105
	v_cvt_pk_bf16_f32 v136, v137, v136
	v_pk_add_f32 v[104:105], v[104:105], 1.0 op_sel_hi:[1,0]
	s_nop 0
	s_nop 0
	v_rcp_f32_e32 v105, v105
	s_nop 0
	v_rcp_f32_e32 v104, v104
	s_nop 0
	v_cvt_pk_bf16_f32 v137, v104, v105
	global_load_dwordx4 v[104:107], v[134:135], off offset:224
	s_waitcnt vmcnt(0)
	v_add_f32_e32 v108, v108, v104
	v_add_f32_e32 v109, v109, v105
	v_mul_f32_e32 v108, 0xbfb8aa3b, v108
	v_mul_f32_e32 v109, 0xbfb8aa3b, v109
	v_exp_f32_e32 v108, v108
	v_exp_f32_e32 v109, v109
	s_nop 0
	v_pk_add_f32 v[108:109], v[108:109], 1.0 op_sel_hi:[1,0]
	s_nop 0
	s_nop 0
	v_rcp_f32_e32 v134, v109
	s_nop 0
	v_rcp_f32_e32 v135, v108
	v_add_f32_e32 v108, v110, v106
	v_add_f32_e32 v109, v111, v107
	v_mul_f32_e32 v108, 0xbfb8aa3b, v108
	v_mul_f32_e32 v109, 0xbfb8aa3b, v109
	v_exp_f32_e32 v108, v108
	v_exp_f32_e32 v109, v109
	s_nop 0
	v_pk_add_f32 v[108:109], v[108:109], 1.0 op_sel_hi:[1,0]
	s_nop 0
	s_nop 0
	v_rcp_f32_e32 v109, v109
	s_nop 0
	v_rcp_f32_e32 v110, v108
	v_cvt_pk_bf16_f32 v108, v135, v134
	v_cvt_pk_bf16_f32 v109, v110, v109
	ds_write2_b64 v132, v[136:137], v[108:109] offset0:12 offset1:14
	s_nop 0
	v_rcp_f32_e32 v108, v81
	s_nop 0
	v_rcp_f32_e32 v109, v80
	v_add_f32_e32 v80, v82, v130
	v_add_f32_e32 v81, v83, v131
	v_mul_f32_e32 v80, 0xbfb8aa3b, v80
	v_mul_f32_e32 v81, 0xbfb8aa3b, v81
	v_exp_f32_e32 v80, v80
	v_exp_f32_e32 v81, v81
	s_nop 0
	v_pk_add_f32 v[80:81], v[80:81], 1.0 op_sel_hi:[1,0]
	s_nop 0
	s_nop 0
	v_rcp_f32_e32 v81, v81
	s_nop 0
	v_rcp_f32_e32 v80, v80
	s_nop 0
	v_cvt_pk_bf16_f32 v83, v80, v81
	v_add_f32_e32 v80, v84, v112
	v_add_f32_e32 v81, v85, v113
	v_mul_f32_e32 v80, 0xbfb8aa3b, v80
	v_mul_f32_e32 v81, 0xbfb8aa3b, v81
	v_exp_f32_e32 v80, v80
	v_exp_f32_e32 v81, v81
	v_cvt_pk_bf16_f32 v82, v109, v108
	v_pk_add_f32 v[80:81], v[80:81], 1.0 op_sel_hi:[1,0]
	s_nop 0
	s_nop 0
	v_rcp_f32_e32 v84, v81
	s_nop 0
	v_rcp_f32_e32 v85, v80
	v_add_f32_e32 v80, v86, v114
	v_add_f32_e32 v81, v87, v115
	v_mul_f32_e32 v80, 0xbfb8aa3b, v80
	v_mul_f32_e32 v81, 0xbfb8aa3b, v81
	v_exp_f32_e32 v80, v80
	v_exp_f32_e32 v81, v81
	v_cvt_pk_bf16_f32 v84, v85, v84
	v_pk_add_f32 v[80:81], v[80:81], 1.0 op_sel_hi:[1,0]
	s_nop 0
	s_nop 0
	v_rcp_f32_e32 v81, v81
	s_nop 0
	v_rcp_f32_e32 v80, v80
	s_nop 0
	v_cvt_pk_bf16_f32 v85, v80, v81
	v_add_f32_e32 v81, v88, v116
	v_add_u32_e32 v80, 0x4000, v132
	v_mul_f32_e32 v81, 0xbfb8aa3b, v81
	ds_write2_b64 v80, v[82:83], v[84:85] offset0:64 offset1:66
	v_exp_f32_e32 v82, v81
	v_add_f32_e32 v81, v89, v117
	v_mul_f32_e32 v81, 0xbfb8aa3b, v81
	v_exp_f32_e32 v83, v81
	s_nop 0
	v_pk_add_f32 v[82:83], v[82:83], 1.0 op_sel_hi:[1,0]
	s_nop 0
	s_nop 0
	v_rcp_f32_e32 v81, v83
	s_nop 0
	v_rcp_f32_e32 v84, v82
	v_add_f32_e32 v82, v90, v118
	v_add_f32_e32 v83, v91, v119
	v_mul_f32_e32 v82, 0xbfb8aa3b, v82
	v_mul_f32_e32 v83, 0xbfb8aa3b, v83
	v_exp_f32_e32 v82, v82
	v_exp_f32_e32 v83, v83
	s_nop 0
	v_pk_add_f32 v[82:83], v[82:83], 1.0 op_sel_hi:[1,0]
	s_nop 0
	s_nop 0
	v_rcp_f32_e32 v83, v83
	s_nop 0
	v_rcp_f32_e32 v85, v82
	v_cvt_pk_bf16_f32 v82, v84, v81
	v_add_f32_e32 v81, v92, v120
	v_mul_f32_e32 v81, 0xbfb8aa3b, v81
	v_exp_f32_e32 v84, v81
	v_add_f32_e32 v81, v93, v121
	v_mul_f32_e32 v81, 0xbfb8aa3b, v81
	v_cvt_pk_bf16_f32 v83, v85, v83
	v_exp_f32_e32 v85, v81
	s_nop 0
	v_pk_add_f32 v[84:85], v[84:85], 1.0 op_sel_hi:[1,0]
	s_nop 0
	s_nop 0
	v_rcp_f32_e32 v81, v85
	s_nop 0
	v_rcp_f32_e32 v86, v84
	v_add_f32_e32 v84, v94, v122
	v_add_f32_e32 v85, v95, v123
	v_mul_f32_e32 v84, 0xbfb8aa3b, v84
	v_mul_f32_e32 v85, 0xbfb8aa3b, v85
	v_exp_f32_e32 v84, v84
	v_exp_f32_e32 v85, v85
	s_nop 0
	v_pk_add_f32 v[84:85], v[84:85], 1.0 op_sel_hi:[1,0]
	s_nop 0
	s_nop 0
	v_rcp_f32_e32 v85, v85
	s_nop 0
	v_rcp_f32_e32 v87, v84
	v_cvt_pk_bf16_f32 v84, v86, v81
	v_cvt_pk_bf16_f32 v85, v87, v85
	ds_write2_b64 v80, v[82:83], v[84:85] offset0:68 offset1:70
	s_nop 0
	v_rcp_f32_e32 v81, v65
	s_nop 0
	v_rcp_f32_e32 v82, v64
	v_add_f32_e32 v64, v66, v126
	v_add_f32_e32 v65, v67, v127
	v_mul_f32_e32 v64, 0xbfb8aa3b, v64
	v_mul_f32_e32 v65, 0xbfb8aa3b, v65
	v_exp_f32_e32 v64, v64
	v_exp_f32_e32 v65, v65
	s_nop 0
	v_pk_add_f32 v[64:65], v[64:65], 1.0 op_sel_hi:[1,0]
	s_nop 0
	s_nop 0
	v_rcp_f32_e32 v65, v65
	s_nop 0
	v_rcp_f32_e32 v66, v64
	s_nop 0
	v_cvt_pk_bf16_f32 v65, v66, v65
	v_add_f32_e32 v66, v68, v96
	v_add_f32_e32 v67, v69, v97
	v_mul_f32_e32 v66, 0xbfb8aa3b, v66
	v_mul_f32_e32 v67, 0xbfb8aa3b, v67
	v_exp_f32_e32 v66, v66
	v_exp_f32_e32 v67, v67
	v_cvt_pk_bf16_f32 v64, v82, v81
	v_pk_add_f32 v[66:67], v[66:67], 1.0 op_sel_hi:[1,0]
	s_nop 0
	s_nop 0
	v_rcp_f32_e32 v68, v67
	s_nop 0
	v_rcp_f32_e32 v69, v66
	v_add_f32_e32 v66, v70, v98
	v_add_f32_e32 v67, v71, v99
	v_mul_f32_e32 v66, 0xbfb8aa3b, v66
	v_mul_f32_e32 v67, 0xbfb8aa3b, v67
	v_exp_f32_e32 v66, v66
	v_exp_f32_e32 v67, v67
	s_nop 0
	v_pk_add_f32 v[66:67], v[66:67], 1.0 op_sel_hi:[1,0]
	s_nop 0
	s_nop 0
	v_rcp_f32_e32 v67, v67
	s_nop 0
	v_rcp_f32_e32 v70, v66
	v_cvt_pk_bf16_f32 v66, v69, v68
	v_cvt_pk_bf16_f32 v67, v70, v67
	ds_write2_b64 v80, v[64:65], v[66:67] offset0:72 offset1:74
	v_add_f32_e32 v64, v72, v100
	v_add_f32_e32 v65, v73, v101
	v_mul_f32_e32 v64, 0xbfb8aa3b, v64
	v_mul_f32_e32 v65, 0xbfb8aa3b, v65
	v_exp_f32_e32 v64, v64
	v_exp_f32_e32 v65, v65
	s_nop 0
	v_pk_add_f32 v[64:65], v[64:65], 1.0 op_sel_hi:[1,0]
	s_nop 0
	s_nop 0
	v_rcp_f32_e32 v66, v65
	s_nop 0
	v_rcp_f32_e32 v67, v64
	v_add_f32_e32 v64, v74, v102
	v_add_f32_e32 v65, v75, v103
	v_mul_f32_e32 v64, 0xbfb8aa3b, v64
	v_mul_f32_e32 v65, 0xbfb8aa3b, v65
	v_exp_f32_e32 v64, v64
	v_exp_f32_e32 v65, v65
	s_nop 0
	v_pk_add_f32 v[64:65], v[64:65], 1.0 op_sel_hi:[1,0]
	s_nop 0
	s_nop 0
	v_rcp_f32_e32 v65, v65
	s_nop 0
	v_rcp_f32_e32 v68, v64
	v_cvt_pk_bf16_f32 v64, v67, v66
	v_add_f32_e32 v66, v76, v104
	v_add_f32_e32 v67, v77, v105
	v_mul_f32_e32 v66, 0xbfb8aa3b, v66
	v_mul_f32_e32 v67, 0xbfb8aa3b, v67
	v_exp_f32_e32 v66, v66
	v_exp_f32_e32 v67, v67
	v_cvt_pk_bf16_f32 v65, v68, v65
	v_pk_add_f32 v[66:67], v[66:67], 1.0 op_sel_hi:[1,0]
	s_nop 0
	s_nop 0
	v_rcp_f32_e32 v68, v67
	s_nop 0
	v_rcp_f32_e32 v69, v66
	v_add_f32_e32 v66, v78, v106
	v_add_f32_e32 v67, v79, v107
	v_mul_f32_e32 v66, 0xbfb8aa3b, v66
	v_mul_f32_e32 v67, 0xbfb8aa3b, v67
	v_exp_f32_e32 v66, v66
	v_exp_f32_e32 v67, v67
	s_nop 0
	v_pk_add_f32 v[66:67], v[66:67], 1.0 op_sel_hi:[1,0]
	s_nop 0
	s_nop 0
	v_rcp_f32_e32 v67, v67
	s_nop 0
	v_rcp_f32_e32 v70, v66
	v_cvt_pk_bf16_f32 v66, v69, v68
	v_cvt_pk_bf16_f32 v67, v70, v67
	ds_write2_b64 v80, v[64:65], v[66:67] offset0:76 offset1:78
	s_nop 0
	v_rcp_f32_e32 v64, v49
	s_nop 0
	v_rcp_f32_e32 v65, v48
	v_add_f32_e32 v48, v50, v130
	v_add_f32_e32 v49, v51, v131
	v_mul_f32_e32 v48, 0xbfb8aa3b, v48
	v_mul_f32_e32 v49, 0xbfb8aa3b, v49
	v_exp_f32_e32 v48, v48
	v_exp_f32_e32 v49, v49
	s_nop 0
	v_pk_add_f32 v[48:49], v[48:49], 1.0 op_sel_hi:[1,0]
	s_nop 0
	s_nop 0
	v_rcp_f32_e32 v49, v49
	s_nop 0
	v_rcp_f32_e32 v48, v48
	s_nop 0
	v_cvt_pk_bf16_f32 v51, v48, v49
	v_add_f32_e32 v48, v52, v112
	v_add_f32_e32 v49, v53, v113
	v_mul_f32_e32 v48, 0xbfb8aa3b, v48
	v_mul_f32_e32 v49, 0xbfb8aa3b, v49
	v_exp_f32_e32 v48, v48
	v_exp_f32_e32 v49, v49
	v_cvt_pk_bf16_f32 v50, v65, v64
	v_pk_add_f32 v[48:49], v[48:49], 1.0 op_sel_hi:[1,0]
	s_nop 0
	s_nop 0
	v_rcp_f32_e32 v52, v49
	s_nop 0
	v_rcp_f32_e32 v53, v48
	v_add_f32_e32 v48, v54, v114
	v_add_f32_e32 v49, v55, v115
	v_mul_f32_e32 v48, 0xbfb8aa3b, v48
	v_mul_f32_e32 v49, 0xbfb8aa3b, v49
	v_exp_f32_e32 v48, v48
	v_exp_f32_e32 v49, v49
	v_cvt_pk_bf16_f32 v52, v53, v52
	v_pk_add_f32 v[48:49], v[48:49], 1.0 op_sel_hi:[1,0]
	s_nop 0
	s_nop 0
	v_rcp_f32_e32 v49, v49
	s_nop 0
	v_rcp_f32_e32 v48, v48
	s_nop 0
	v_cvt_pk_bf16_f32 v53, v48, v49
	v_add_f32_e32 v49, v56, v116
	v_add_u32_e32 v48, 0x8000, v132
	v_mul_f32_e32 v49, 0xbfb8aa3b, v49
	ds_write2_b64 v48, v[50:51], v[52:53] offset0:128 offset1:130
	v_exp_f32_e32 v50, v49
	v_add_f32_e32 v49, v57, v117
	v_mul_f32_e32 v49, 0xbfb8aa3b, v49
	v_exp_f32_e32 v51, v49
	s_nop 0
	v_pk_add_f32 v[50:51], v[50:51], 1.0 op_sel_hi:[1,0]
	s_nop 0
	s_nop 0
	v_rcp_f32_e32 v49, v51
	s_nop 0
	v_rcp_f32_e32 v52, v50
	v_add_f32_e32 v50, v58, v118
	v_add_f32_e32 v51, v59, v119
	v_mul_f32_e32 v50, 0xbfb8aa3b, v50
	v_mul_f32_e32 v51, 0xbfb8aa3b, v51
	v_exp_f32_e32 v50, v50
	v_exp_f32_e32 v51, v51
	s_nop 0
	v_pk_add_f32 v[50:51], v[50:51], 1.0 op_sel_hi:[1,0]
	s_nop 0
	s_nop 0
	v_rcp_f32_e32 v51, v51
	s_nop 0
	v_rcp_f32_e32 v53, v50
	v_cvt_pk_bf16_f32 v50, v52, v49
	v_add_f32_e32 v49, v60, v120
	v_mul_f32_e32 v49, 0xbfb8aa3b, v49
	v_exp_f32_e32 v52, v49
	v_add_f32_e32 v49, v61, v121
	v_mul_f32_e32 v49, 0xbfb8aa3b, v49
	v_cvt_pk_bf16_f32 v51, v53, v51
	v_exp_f32_e32 v53, v49
	s_nop 0
	v_pk_add_f32 v[52:53], v[52:53], 1.0 op_sel_hi:[1,0]
	s_nop 0
	s_nop 0
	v_rcp_f32_e32 v49, v53
	s_nop 0
	v_rcp_f32_e32 v54, v52
	v_add_f32_e32 v52, v62, v122
	v_add_f32_e32 v53, v63, v123
	v_mul_f32_e32 v52, 0xbfb8aa3b, v52
	v_mul_f32_e32 v53, 0xbfb8aa3b, v53
	v_exp_f32_e32 v52, v52
	v_exp_f32_e32 v53, v53
	s_nop 0
	v_pk_add_f32 v[52:53], v[52:53], 1.0 op_sel_hi:[1,0]
	s_nop 0
	s_nop 0
	v_rcp_f32_e32 v53, v53
	s_nop 0
	v_rcp_f32_e32 v55, v52
	v_cvt_pk_bf16_f32 v52, v54, v49
	v_cvt_pk_bf16_f32 v53, v55, v53
	ds_write2_b64 v48, v[50:51], v[52:53] offset0:132 offset1:134
	s_nop 0
	v_rcp_f32_e32 v49, v33
	s_nop 0
	v_rcp_f32_e32 v50, v32
	v_add_f32_e32 v32, v34, v126
	v_add_f32_e32 v33, v35, v127
	v_mul_f32_e32 v32, 0xbfb8aa3b, v32
	v_mul_f32_e32 v33, 0xbfb8aa3b, v33
	v_exp_f32_e32 v32, v32
	v_exp_f32_e32 v33, v33
	s_nop 0
	v_pk_add_f32 v[32:33], v[32:33], 1.0 op_sel_hi:[1,0]
	s_nop 0
	s_nop 0
	v_rcp_f32_e32 v33, v33
	s_nop 0
	v_rcp_f32_e32 v34, v32
	s_nop 0
	v_cvt_pk_bf16_f32 v33, v34, v33
	v_add_f32_e32 v34, v36, v96
	v_add_f32_e32 v35, v37, v97
	v_mul_f32_e32 v34, 0xbfb8aa3b, v34
	v_mul_f32_e32 v35, 0xbfb8aa3b, v35
	v_exp_f32_e32 v34, v34
	v_exp_f32_e32 v35, v35
	v_cvt_pk_bf16_f32 v32, v50, v49
	v_pk_add_f32 v[34:35], v[34:35], 1.0 op_sel_hi:[1,0]
	s_nop 0
	s_nop 0
	v_rcp_f32_e32 v36, v35
	s_nop 0
	v_rcp_f32_e32 v37, v34
	v_add_f32_e32 v34, v38, v98
	v_add_f32_e32 v35, v39, v99
	v_mul_f32_e32 v34, 0xbfb8aa3b, v34
	v_mul_f32_e32 v35, 0xbfb8aa3b, v35
	v_exp_f32_e32 v34, v34
	v_exp_f32_e32 v35, v35
	s_nop 0
	v_pk_add_f32 v[34:35], v[34:35], 1.0 op_sel_hi:[1,0]
	s_nop 0
	s_nop 0
	v_rcp_f32_e32 v35, v35
	s_nop 0
	v_rcp_f32_e32 v38, v34
	v_cvt_pk_bf16_f32 v34, v37, v36
	v_cvt_pk_bf16_f32 v35, v38, v35
	ds_write2_b64 v48, v[32:33], v[34:35] offset0:136 offset1:138
	v_add_f32_e32 v32, v40, v100
	v_add_f32_e32 v33, v41, v101
	v_mul_f32_e32 v32, 0xbfb8aa3b, v32
	v_mul_f32_e32 v33, 0xbfb8aa3b, v33
	v_exp_f32_e32 v32, v32
	v_exp_f32_e32 v33, v33
	s_nop 0
	v_pk_add_f32 v[32:33], v[32:33], 1.0 op_sel_hi:[1,0]
	s_nop 0
	s_nop 0
	v_rcp_f32_e32 v34, v33
	s_nop 0
	v_rcp_f32_e32 v35, v32
	v_add_f32_e32 v32, v42, v102
	v_add_f32_e32 v33, v43, v103
	v_mul_f32_e32 v32, 0xbfb8aa3b, v32
	v_mul_f32_e32 v33, 0xbfb8aa3b, v33
	v_exp_f32_e32 v32, v32
	v_exp_f32_e32 v33, v33
	s_nop 0
	v_pk_add_f32 v[32:33], v[32:33], 1.0 op_sel_hi:[1,0]
	s_nop 0
	s_nop 0
	v_rcp_f32_e32 v33, v33
	s_nop 0
	v_rcp_f32_e32 v36, v32
	v_cvt_pk_bf16_f32 v32, v35, v34
	v_add_f32_e32 v34, v44, v104
	v_add_f32_e32 v35, v45, v105
	v_mul_f32_e32 v34, 0xbfb8aa3b, v34
	v_mul_f32_e32 v35, 0xbfb8aa3b, v35
	v_exp_f32_e32 v34, v34
	v_exp_f32_e32 v35, v35
	v_cvt_pk_bf16_f32 v33, v36, v33
	v_pk_add_f32 v[34:35], v[34:35], 1.0 op_sel_hi:[1,0]
	s_nop 0
	s_nop 0
	v_rcp_f32_e32 v36, v35
	s_nop 0
	v_rcp_f32_e32 v37, v34
	v_add_f32_e32 v34, v46, v106
	v_add_f32_e32 v35, v47, v107
	v_mul_f32_e32 v34, 0xbfb8aa3b, v34
	v_mul_f32_e32 v35, 0xbfb8aa3b, v35
	v_exp_f32_e32 v34, v34
	v_exp_f32_e32 v35, v35
	s_nop 0
	v_pk_add_f32 v[34:35], v[34:35], 1.0 op_sel_hi:[1,0]
	s_nop 0
	s_nop 0
	v_rcp_f32_e32 v35, v35
	s_nop 0
	v_rcp_f32_e32 v38, v34
	v_cvt_pk_bf16_f32 v34, v37, v36
	v_cvt_pk_bf16_f32 v35, v38, v35
	ds_write2_b64 v48, v[32:33], v[34:35] offset0:140 offset1:142
	s_nop 0
	v_rcp_f32_e32 v32, v17
	s_nop 0
	v_rcp_f32_e32 v33, v16
	v_add_f32_e32 v16, v18, v130
	v_add_f32_e32 v17, v19, v131
	v_mul_f32_e32 v16, 0xbfb8aa3b, v16
	v_mul_f32_e32 v17, 0xbfb8aa3b, v17
	v_exp_f32_e32 v16, v16
	v_exp_f32_e32 v17, v17
	s_nop 0
	v_pk_add_f32 v[16:17], v[16:17], 1.0 op_sel_hi:[1,0]
	s_nop 0
	s_nop 0
	v_rcp_f32_e32 v17, v17
	s_nop 0
	v_rcp_f32_e32 v16, v16
	s_nop 0
	v_cvt_pk_bf16_f32 v19, v16, v17
	v_add_f32_e32 v16, v20, v112
	v_add_f32_e32 v17, v21, v113
	v_mul_f32_e32 v16, 0xbfb8aa3b, v16
	v_mul_f32_e32 v17, 0xbfb8aa3b, v17
	v_exp_f32_e32 v16, v16
	v_exp_f32_e32 v17, v17
	v_cvt_pk_bf16_f32 v18, v33, v32
	v_pk_add_f32 v[16:17], v[16:17], 1.0 op_sel_hi:[1,0]
	s_nop 0
	s_nop 0
	v_rcp_f32_e32 v20, v17
	s_nop 0
	v_rcp_f32_e32 v21, v16
	v_add_f32_e32 v16, v22, v114
	v_add_f32_e32 v17, v23, v115
	v_mul_f32_e32 v16, 0xbfb8aa3b, v16
	v_mul_f32_e32 v17, 0xbfb8aa3b, v17
	v_exp_f32_e32 v16, v16
	v_exp_f32_e32 v17, v17
	v_cvt_pk_bf16_f32 v20, v21, v20
	v_pk_add_f32 v[16:17], v[16:17], 1.0 op_sel_hi:[1,0]
	s_nop 0
	s_nop 0
	v_rcp_f32_e32 v17, v17
	s_nop 0
	v_rcp_f32_e32 v16, v16
	s_nop 0
	v_cvt_pk_bf16_f32 v21, v16, v17
	v_add_f32_e32 v17, v24, v116
	v_add_u32_e32 v16, 0xc000, v132
	v_mul_f32_e32 v17, 0xbfb8aa3b, v17
	ds_write2_b64 v16, v[18:19], v[20:21] offset0:192 offset1:194
	v_exp_f32_e32 v18, v17
	v_add_f32_e32 v17, v25, v117
	v_mul_f32_e32 v17, 0xbfb8aa3b, v17
	v_exp_f32_e32 v19, v17
	s_nop 0
	v_pk_add_f32 v[18:19], v[18:19], 1.0 op_sel_hi:[1,0]
	s_nop 0
	s_nop 0
	v_rcp_f32_e32 v17, v19
	s_nop 0
	v_rcp_f32_e32 v20, v18
	v_add_f32_e32 v18, v26, v118
	v_add_f32_e32 v19, v27, v119
	v_mul_f32_e32 v18, 0xbfb8aa3b, v18
	v_mul_f32_e32 v19, 0xbfb8aa3b, v19
	v_exp_f32_e32 v18, v18
	v_exp_f32_e32 v19, v19
	s_nop 0
	v_pk_add_f32 v[18:19], v[18:19], 1.0 op_sel_hi:[1,0]
	s_nop 0
	s_nop 0
	v_rcp_f32_e32 v19, v19
	s_nop 0
	v_rcp_f32_e32 v21, v18
	v_cvt_pk_bf16_f32 v18, v20, v17
	v_add_f32_e32 v17, v28, v120
	v_mul_f32_e32 v17, 0xbfb8aa3b, v17
	v_exp_f32_e32 v20, v17
	v_add_f32_e32 v17, v29, v121
	v_mul_f32_e32 v17, 0xbfb8aa3b, v17
	v_cvt_pk_bf16_f32 v19, v21, v19
	v_exp_f32_e32 v21, v17
	s_nop 0
	v_pk_add_f32 v[20:21], v[20:21], 1.0 op_sel_hi:[1,0]
	s_nop 0
	s_nop 0
	v_rcp_f32_e32 v17, v21
	s_nop 0
	v_rcp_f32_e32 v22, v20
	v_add_f32_e32 v20, v30, v122
	v_add_f32_e32 v21, v31, v123
	v_mul_f32_e32 v20, 0xbfb8aa3b, v20
	v_mul_f32_e32 v21, 0xbfb8aa3b, v21
	v_exp_f32_e32 v20, v20
	v_exp_f32_e32 v21, v21
	s_nop 0
	v_pk_add_f32 v[20:21], v[20:21], 1.0 op_sel_hi:[1,0]
	s_nop 0
	s_nop 0
	v_rcp_f32_e32 v21, v21
	s_nop 0
	v_rcp_f32_e32 v23, v20
	v_cvt_pk_bf16_f32 v20, v22, v17
	v_cvt_pk_bf16_f32 v21, v23, v21
	ds_write2_b64 v16, v[18:19], v[20:21] offset0:196 offset1:198
	s_nop 0
	v_rcp_f32_e32 v17, v1
	s_nop 0
	v_rcp_f32_e32 v18, v0
	v_add_f32_e32 v0, v2, v126
	v_add_f32_e32 v1, v3, v127
	v_mul_f32_e32 v0, 0xbfb8aa3b, v0
	v_mul_f32_e32 v1, 0xbfb8aa3b, v1
	v_exp_f32_e32 v0, v0
	v_exp_f32_e32 v1, v1
	s_nop 0
	v_pk_add_f32 v[0:1], v[0:1], 1.0 op_sel_hi:[1,0]
	s_nop 0
	s_nop 0
	v_rcp_f32_e32 v1, v1
	s_nop 0
	v_rcp_f32_e32 v2, v0
	s_nop 0
	v_cvt_pk_bf16_f32 v1, v2, v1
	v_add_f32_e32 v2, v4, v96
	v_add_f32_e32 v3, v5, v97
	v_mul_f32_e32 v2, 0xbfb8aa3b, v2
	v_mul_f32_e32 v3, 0xbfb8aa3b, v3
	v_exp_f32_e32 v2, v2
	v_exp_f32_e32 v3, v3
	v_cvt_pk_bf16_f32 v0, v18, v17
	v_pk_add_f32 v[2:3], v[2:3], 1.0 op_sel_hi:[1,0]
	s_nop 0
	s_nop 0
	v_rcp_f32_e32 v4, v3
	s_nop 0
	v_rcp_f32_e32 v5, v2
	v_add_f32_e32 v2, v6, v98
	v_add_f32_e32 v3, v7, v99
	v_mul_f32_e32 v2, 0xbfb8aa3b, v2
	v_mul_f32_e32 v3, 0xbfb8aa3b, v3
	v_exp_f32_e32 v2, v2
	v_exp_f32_e32 v3, v3
	s_nop 0
	v_pk_add_f32 v[2:3], v[2:3], 1.0 op_sel_hi:[1,0]
	s_nop 0
	s_nop 0
	v_rcp_f32_e32 v3, v3
	s_nop 0
	v_rcp_f32_e32 v6, v2
	v_cvt_pk_bf16_f32 v2, v5, v4
	v_cvt_pk_bf16_f32 v3, v6, v3
	ds_write2_b64 v16, v[0:1], v[2:3] offset0:200 offset1:202
	v_add_f32_e32 v0, v8, v100
	v_add_f32_e32 v1, v9, v101
	v_mul_f32_e32 v0, 0xbfb8aa3b, v0
	v_mul_f32_e32 v1, 0xbfb8aa3b, v1
	v_exp_f32_e32 v0, v0
	v_exp_f32_e32 v1, v1
	s_nop 0
	v_pk_add_f32 v[0:1], v[0:1], 1.0 op_sel_hi:[1,0]
	s_nop 0
	s_nop 0
	v_rcp_f32_e32 v2, v1
	s_nop 0
	v_rcp_f32_e32 v3, v0
	v_add_f32_e32 v0, v10, v102
	v_add_f32_e32 v1, v11, v103
	v_mul_f32_e32 v0, 0xbfb8aa3b, v0
	v_mul_f32_e32 v1, 0xbfb8aa3b, v1
	v_exp_f32_e32 v0, v0
	v_exp_f32_e32 v1, v1
	s_nop 0
	v_pk_add_f32 v[0:1], v[0:1], 1.0 op_sel_hi:[1,0]
	s_nop 0
	s_nop 0
	v_rcp_f32_e32 v1, v1
	s_nop 0
	v_rcp_f32_e32 v4, v0
	v_cvt_pk_bf16_f32 v0, v3, v2
	v_add_f32_e32 v2, v12, v104
	v_add_f32_e32 v3, v13, v105
	v_mul_f32_e32 v2, 0xbfb8aa3b, v2
	v_mul_f32_e32 v3, 0xbfb8aa3b, v3
	v_exp_f32_e32 v2, v2
	v_exp_f32_e32 v3, v3
	v_cvt_pk_bf16_f32 v1, v4, v1
	v_pk_add_f32 v[2:3], v[2:3], 1.0 op_sel_hi:[1,0]
	s_nop 0
	s_nop 0
	v_rcp_f32_e32 v4, v3
	s_nop 0
	v_rcp_f32_e32 v5, v2
	v_add_f32_e32 v2, v14, v106
	v_add_f32_e32 v3, v15, v107
	v_mul_f32_e32 v2, 0xbfb8aa3b, v2
	v_mul_f32_e32 v3, 0xbfb8aa3b, v3
	v_exp_f32_e32 v2, v2
	v_exp_f32_e32 v3, v3
	s_nop 0
	v_pk_add_f32 v[2:3], v[2:3], 1.0 op_sel_hi:[1,0]
	s_nop 0
	s_nop 0
	v_rcp_f32_e32 v3, v3
	s_nop 0
	v_rcp_f32_e32 v6, v2
	v_cvt_pk_bf16_f32 v2, v5, v4
	v_cvt_pk_bf16_f32 v3, v6, v3
	ds_write2_b64 v16, v[0:1], v[2:3] offset0:204 offset1:206
	v_mov_b32_e32 v1, v176
	s_waitcnt lgkmcnt(0)
	s_barrier
	s_nop 0
	v_lshlrev_b32_e32 v0, 3, v1
	v_and_b32_e32 v0, 0xf8, v0
	v_or_b32_e32 v2, s62, v0
	v_lshlrev_b32_e32 v132, 1, v2
	v_lshlrev_b32_e32 v0, 1, v0
	v_lshl_add_u64 v[2:3], s[52:53], 0, v[132:133]
